# GEMM3 tile order: the two workgroups of a CU (adjacent virtual ids) now share the A row block instead of the B column block
# speedup vs baseline: 1.0041x; 1.0017x over previous
; template <int MODE>
; __device__ __forceinline__ void gemm_tile(const Params& P, int tm, int tn, unsigned char* smem) {
;     ...
;     const int tid = opaque_tid(), lane = tid & 63, wave = tid >> 6, wr = wave >> 1, wc = wave & 1, g = lane >> 4, lr = lane & 15;
;     const int m0 = tm * 128, n0 = tn * 128;
;     const int srow = tid >> 3, sc = tid & 7;
;     constexpr unsigned LDA = (MODE == 2 ? NZ : 1024) * 2u;
;     unsigned aoff, boff; int soff0;
;     {
;         int ar = m0 + srow;
;         if (MODE == 2) { const int b = ar >> 11, t = ar & 2047; ar = b * L + NMETA + t; }
;         aoff = (unsigned)ar * LDA + (unsigned)sc * 16u;
;         boff = (unsigned)(n0 + srow) * 2048u + (unsigned)sc * 16u;
;         soff0 = srow * 128 + ((sc ^ (srow & 7)) << 4);
;     }
;     const unsigned char* Ab = (const unsigned char*)A; const unsigned char* Bb = (const unsigned char*)Bt;
;     float4 ssp0, ssp1, ssp2, ssp3;
;     if (MODE == 3) {
;         const float* ssq = (const float*)(P.ws + WS_SSQ) + (size_t)(m0 + wr * 64 + lr) * 16 + 4 * g;
;         ssp0 = *(const float4*)(ssq); ssp1 = *(const float4*)(ssq + 16 * 16); ssp2 = *(const float4*)(ssq + 32 * 16); ssp3 = *(const float4*)(ssq + 48 * 16);
;     }
;     f32x4 acc[4][4];
; #pragma unroll
;     for (int i = 0; i < 4; ++i)
; #pragma unroll
;         for (int j = 0; j < 4; ++j) acc[i][j] = (f32x4){0.f, 0.f, 0.f, 0.f};
;     uint4 ra0, ra1, ra2, ra3, rb0, rb1, rb2, rb3;
;     ...
;     unsigned char* sA0 = smem; unsigned char* sB0 = smem + 16384; unsigned char* sA1 = smem + 32768; unsigned char* sB1 = smem + 49152;
;     G_LOAD(0)
;     G_WRITE(sA0, sB0)
;     __syncthreads();
;     const int arow_off = (wr * 64 + lr) * 128, brow_off = (wc * 64 + lr) * 128, sw = lr & 7;
;     G_LOAD(1)
;     for (int kt = 0; kt < 16; ++kt) {
;         unsigned char* sA = (kt & 1) ? sA1 : sA0; unsigned char* sB = (kt & 1) ? sB1 : sB0;
;         unsigned char* nA = (kt & 1) ? sA0 : sA1; unsigned char* nB = (kt & 1) ? sB0 : sB1;
;         bf16x8 fa[4], fb[4], ga[4], gb[4];
;         const int ch0 = ((g ^ sw) << 4), ch1 = (((4 + g) ^ sw) << 4);
;         const unsigned ko = (unsigned)(kt + 2) * 128u;
;         const unsigned koa = ko + ((MODE == 2 && kt + 2 >= 8) ? (unsigned)(ZC_FQ - 512) * 2u : 0u);
;         const bool wr_ok = kt < 15, ld_ok = kt < 14;
; #pragma unroll
.LBB0_1263:
	s_lshr_b32 s0, s14, 4
	s_and_b32 s0, s0, 0x1fffff8
	s_bfe_u32 s1, s14, 0x30001
	s_or_b32 s0, s0, s1
	v_mov_b32_e32 v88, v0
	s_bfe_u32 s2, s14, 0x30004
	s_and_b32 s92, s14, 1
	s_lshl_b32 s2, s2, 1
	s_or_b32 s2, s2, s92
	s_lshl_b32 s23, s0, 7
	v_ashrrev_i32_e32 v6, 3, v88
	v_lshlrev_b32_e32 v3, 4, v88
	v_add_u32_e32 v2, s23, v6
	v_and_b32_e32 v3, 0x70, v3
	s_lshl_b32 s0, s2, 18
	v_lshl_add_u32 v4, v6, 11, s0
	v_lshl_or_b32 v24, v2, 11, v3
	v_or_b32_e32 v18, v4, v3
	v_add_u32_e32 v2, 0x10000, v24
	v_add_u32_e32 v3, 0x20000, v24
	global_load_dwordx4 v[20:23], v2, s[36:37]
	global_load_dwordx4 v[26:29], v3, s[36:37]
	v_add_u32_e32 v2, 0x20000, v18
	v_add_u32_e32 v3, 0x30000, v18
	global_load_dwordx4 v[30:33], v2, s[6:7]
	global_load_dwordx4 v[34:37], v3, s[6:7]
	v_add_u32_e32 v2, 0x30000, v24
	v_add_u32_e32 v3, 0x10000, v18
	global_load_dwordx4 v[38:41], v2, s[36:37]
	global_load_dwordx4 v[42:45], v3, s[6:7]
	global_load_dwordx4 v[46:49], v24, s[36:37]
	global_load_dwordx4 v[50:53], v18, s[6:7]
	v_ashrrev_i32_e32 v2, 1, v88
	v_and_b32_e32 v25, 0xffffffc0, v2
	v_and_b32_e32 v90, 15, v88
	v_add_u32_e32 v2, s23, v25
	v_or_b32_e32 v84, v2, v90
	v_ashrrev_i32_e32 v85, 31, v84
	v_xor_b32_e32 v7, v6, v88
	v_bfe_u32 v89, v88, 4, 2
	v_lshlrev_b64 v[2:3], 6, v[84:85]
	v_lshlrev_b32_e32 v6, 7, v6
	v_lshlrev_b32_e32 v7, 4, v7
	v_lshlrev_b32_e32 v82, 4, v89
	v_lshl_add_u64 v[2:3], s[4:5], 0, v[2:3]
	v_and_or_b32 v6, v7, s15, v6
	v_lshl_add_u64 v[54:55], v[2:3], 0, v[82:83]
	v_add_u32_e32 v19, 0, v6
	v_or_b32_e32 v62, 0x80, v24
	global_load_dwordx4 v[10:13], v[54:55], off
	global_load_dwordx4 v[2:5], v[54:55], off offset:3072
	v_or_b32_e32 v58, 0x80, v18
	v_add_u32_e32 v59, 0x10080, v18
	v_add_u32_e32 v60, 0x20080, v18
	v_add_u32_e32 v61, 0x30080, v18
	v_add_u32_e32 v63, 0x10080, v24
	v_add_u32_e32 v64, 0x20080, v24
	v_add_u32_e32 v65, 0x30080, v24
	global_load_dwordx4 v[14:17], v[54:55], off offset:1024
	global_load_dwordx4 v[6:9], v[54:55], off offset:2048
	v_or_b32_e32 v82, v25, v90
	v_and_b32_e32 v25, 7, v88
	v_bfe_u32 v91, v88, 6, 1
	v_lshl_add_u32 v104, v82, 7, 0
	s_waitcnt vmcnt(9)
	ds_write_b128 v19, v[30:33] offset:24576
	s_waitcnt vmcnt(8)
	ds_write_b128 v19, v[34:37] offset:28672
	ds_write_b128 v19, v[20:23] offset:4096
	ds_write_b128 v19, v[26:29] offset:8192
	s_waitcnt vmcnt(7)
	ds_write_b128 v19, v[38:41] offset:12288
	s_waitcnt vmcnt(6)
	ds_write_b128 v19, v[42:45] offset:20480
	s_waitcnt vmcnt(5)
	ds_write_b128 v19, v[46:49]
	s_waitcnt vmcnt(4)
	ds_write_b128 v19, v[50:53] offset:16384
	s_waitcnt lgkmcnt(0)
	s_barrier
	global_load_dwordx4 v[26:29], v62, s[36:37]
	global_load_dwordx4 v[30:33], v63, s[36:37]
	global_load_dwordx4 v[34:37], v64, s[36:37]
	global_load_dwordx4 v[38:41], v65, s[36:37]
	global_load_dwordx4 v[42:45], v58, s[6:7]
	global_load_dwordx4 v[46:49], v59, s[6:7]
	global_load_dwordx4 v[50:53], v60, s[6:7]
	global_load_dwordx4 v[54:57], v61, s[6:7]
	v_lshrrev_b32_e32 v20, 4, v88
	v_lshlrev_b32_e32 v21, 7, v90
	v_bitop3_b32 v20, v20, v25, 3 bitop3:0x6c
	v_lshl_or_b32 v21, v91, 13, v21
	v_lshlrev_b32_e32 v20, 4, v20
	v_add_u32_e32 v22, v104, v20
	v_add_u32_e32 v21, 0, v21
	v_add_u32_e32 v23, v21, v20
	ds_read_b128 v[58:61], v22
	ds_read_b128 v[62:65], v22 offset:2048
	ds_read_b128 v[66:69], v23 offset:16384
	ds_read_b128 v[70:73], v23 offset:18432
	ds_read_b128 v[74:77], v22 offset:4096
	ds_read_b128 v[78:81], v22 offset:6144
	ds_read_b128 v[92:95], v23 offset:20480
	ds_read_b128 v[96:99], v23 offset:22528
	v_bitop3_b32 v20, v89, v25, 4 bitop3:0x36
	v_lshlrev_b32_e32 v25, 4, v20
	s_setprio 2
	global_load_dwordx4 v[100:103], v24, s[36:37] offset:256
	s_waitcnt vmcnt(8)
	ds_write_b128 v19, v[26:29] offset:32768
	v_add_u32_e32 v20, v104, v25
	v_add_u32_e32 v21, v21, v25
	ds_read_b128 v[26:29], v20
	ds_read_b128 v[104:107], v21 offset:16384
	s_waitcnt lgkmcnt(8)
	v_mfma_f32_16x16x32_bf16 v[108:111], v[66:69], v[58:61], 0
	s_waitcnt lgkmcnt(7)
	v_mfma_f32_16x16x32_bf16 v[112:115], v[70:73], v[58:61], 0
	s_waitcnt lgkmcnt(4)
	v_mfma_f32_16x16x32_bf16 v[116:119], v[92:95], v[58:61], 0
	s_waitcnt lgkmcnt(3)
	v_mfma_f32_16x16x32_bf16 v[58:61], v[96:99], v[58:61], 0
	v_add_u32_e32 v245, 0x10000, v24
	global_load_dwordx4 v[120:123], v245, s[36:37] offset:256
	s_waitcnt vmcnt(8)
	ds_write_b128 v19, v[30:33] offset:36864
	ds_read_b128 v[30:33], v20 offset:2048
	ds_read_b128 v[124:127], v21 offset:18432
	v_mfma_f32_16x16x32_bf16 v[132:135], v[66:69], v[62:65], 0
	v_mfma_f32_16x16x32_bf16 v[136:139], v[70:73], v[62:65], 0
	v_mfma_f32_16x16x32_bf16 v[140:143], v[92:95], v[62:65], 0
	v_mfma_f32_16x16x32_bf16 v[62:65], v[96:99], v[62:65], 0
	v_add_u32_e32 v246, 0x20000, v24
	global_load_dwordx4 v[144:147], v246, s[36:37] offset:256
	s_waitcnt vmcnt(8)
	ds_write_b128 v19, v[34:37] offset:40960
	ds_read_b128 v[34:37], v20 offset:4096
	ds_read_b128 v[148:151], v21 offset:20480
	v_mfma_f32_16x16x32_bf16 v[152:155], v[66:69], v[74:77], 0
	v_mfma_f32_16x16x32_bf16 v[156:159], v[70:73], v[74:77], 0
	v_mfma_f32_16x16x32_bf16 v[160:163], v[92:95], v[74:77], 0
	v_mfma_f32_16x16x32_bf16 v[74:77], v[96:99], v[74:77], 0
	v_add_u32_e32 v247, 0x30000, v24
	global_load_dwordx4 v[164:167], v247, s[36:37] offset:256
	s_waitcnt vmcnt(8)
	ds_write_b128 v19, v[38:41] offset:45056
	ds_read_b128 v[38:41], v20 offset:6144
	ds_read_b128 v[168:171], v21 offset:22528
	v_mfma_f32_16x16x32_bf16 v[66:69], v[66:69], v[78:81], 0
	v_mfma_f32_16x16x32_bf16 v[70:73], v[70:73], v[78:81], 0
	v_mfma_f32_16x16x32_bf16 v[92:95], v[92:95], v[78:81], 0
	v_mfma_f32_16x16x32_bf16 v[78:81], v[96:99], v[78:81], 0
	global_load_dwordx4 v[96:99], v18, s[6:7] offset:256
	s_waitcnt vmcnt(8)
; template <int MODE>
; __device__ __forceinline__ void gemm_tile(const Params& P, int tm, int tn, unsigned char* smem) {
;     ...
; #pragma unroll
;         for (int i = 0; i < 4; ++i) { fa[i] = *(const bf16x8*)(sA + arow_off + i * 2048 + ch0); fb[i] = *(const bf16x8*)(sB + brow_off + i * 2048 + ch0); }
;         __builtin_amdgcn_sched_barrier(0);
;         __builtin_amdgcn_s_setprio(2);
;         if (wr_ok) *(uint4*)(nA + soff0) = ra0;
;         if (ld_ok) ra0 = *(const uint4*)(Ab + (aoff + 0u * LDA + koa));
;         ga[0] = *(const bf16x8*)(sA + arow_off + 0 * 2048 + ch1); gb[0] = *(const bf16x8*)(sB + brow_off + 0 * 2048 + ch1);
;         __builtin_amdgcn_sched_barrier(0);
; #pragma unroll
;         for (int j = 0; j < 4; ++j) acc[0][j] = __builtin_amdgcn_mfma_f32_16x16x32_bf16(fb[j], fa[0], acc[0][j], 0, 0, 0);
;         __builtin_amdgcn_sched_barrier(0);
;         if (wr_ok) *(uint4*)(nA + soff0 + 4096) = ra1;
;         if (ld_ok) ra1 = *(const uint4*)(Ab + (aoff + 32u * LDA + koa));
;         ga[1] = *(const bf16x8*)(sA + arow_off + 1 * 2048 + ch1); gb[1] = *(const bf16x8*)(sB + brow_off + 1 * 2048 + ch1);
;         __builtin_amdgcn_sched_barrier(0);
; #pragma unroll
;         for (int j = 0; j < 4; ++j) acc[1][j] = __builtin_amdgcn_mfma_f32_16x16x32_bf16(fb[j], fa[1], acc[1][j], 0, 0, 0);
;         __builtin_amdgcn_sched_barrier(0);
;         if (wr_ok) *(uint4*)(nA + soff0 + 8192) = ra2;
;         if (ld_ok) ra2 = *(const uint4*)(Ab + (aoff + 64u * LDA + koa));
;         ga[2] = *(const bf16x8*)(sA + arow_off + 2 * 2048 + ch1); gb[2] = *(const bf16x8*)(sB + brow_off + 2 * 2048 + ch1);
;         __builtin_amdgcn_sched_barrier(0);
; #pragma unroll
;         for (int j = 0; j < 4; ++j) acc[2][j] = __builtin_amdgcn_mfma_f32_16x16x32_bf16(fb[j], fa[2], acc[2][j], 0, 0, 0);
;         __builtin_amdgcn_sched_barrier(0);
;         if (wr_ok) *(uint4*)(nA + soff0 + 12288) = ra3;
;         if (ld_ok) ra3 = *(const uint4*)(Ab + (aoff + 96u * LDA + koa));
;         ga[3] = *(const bf16x8*)(sA + arow_off + 3 * 2048 + ch1); gb[3] = *(const bf16x8*)(sB + brow_off + 3 * 2048 + ch1);
;         __builtin_amdgcn_sched_barrier(0);
; #pragma unroll
;         for (int j = 0; j < 4; ++j) acc[3][j] = __builtin_amdgcn_mfma_f32_16x16x32_bf16(fb[j], fa[3], acc[3][j], 0, 0, 0);
;         __builtin_amdgcn_sched_barrier(0);
;         if (wr_ok) *(uint4*)(nB + soff0) = rb0;
	ds_write_b128 v19, v[42:45] offset:49152
	s_waitcnt lgkmcnt(10)
	v_mfma_f32_16x16x32_bf16 v[42:45], v[104:107], v[26:29], v[108:111]
	s_waitcnt lgkmcnt(7)
	v_mfma_f32_16x16x32_bf16 v[108:111], v[124:127], v[26:29], v[112:115]
	s_waitcnt lgkmcnt(4)
	v_mfma_f32_16x16x32_bf16 v[112:115], v[148:151], v[26:29], v[116:119]
	s_waitcnt lgkmcnt(1)
	v_mfma_f32_16x16x32_bf16 v[26:29], v[168:171], v[26:29], v[58:61]
	v_add_u32_e32 v248, 0x10000, v18
	global_load_dwordx4 v[58:61], v248, s[6:7] offset:256
	s_waitcnt vmcnt(8)
	ds_write_b128 v19, v[46:49] offset:53248
	v_mfma_f32_16x16x32_bf16 v[46:49], v[104:107], v[30:33], v[132:135]
	v_mfma_f32_16x16x32_bf16 v[116:119], v[124:127], v[30:33], v[136:139]
	v_mfma_f32_16x16x32_bf16 v[132:135], v[148:151], v[30:33], v[140:143]
	v_mfma_f32_16x16x32_bf16 v[30:33], v[168:171], v[30:33], v[62:65]
	v_add_u32_e32 v249, 0x20000, v18
	global_load_dwordx4 v[62:65], v249, s[6:7] offset:256
	s_waitcnt vmcnt(8)
	ds_write_b128 v19, v[50:53] offset:57344
	v_mfma_f32_16x16x32_bf16 v[50:53], v[104:107], v[34:37], v[152:155]
	v_mfma_f32_16x16x32_bf16 v[136:139], v[124:127], v[34:37], v[156:159]
	v_mfma_f32_16x16x32_bf16 v[140:143], v[148:151], v[34:37], v[160:163]
	v_mfma_f32_16x16x32_bf16 v[34:37], v[168:171], v[34:37], v[74:77]
	v_add_u32_e32 v250, 0x30000, v18
	global_load_dwordx4 v[74:77], v250, s[6:7] offset:256
	s_waitcnt vmcnt(8)
	ds_write_b128 v19, v[54:57] offset:61440
	v_mfma_f32_16x16x32_bf16 v[54:57], v[104:107], v[38:41], v[66:69]
	v_mfma_f32_16x16x32_bf16 v[66:69], v[124:127], v[38:41], v[70:73]
	v_mfma_f32_16x16x32_bf16 v[70:73], v[148:151], v[38:41], v[92:95]
	v_mfma_f32_16x16x32_bf16 v[38:41], v[168:171], v[38:41], v[78:81]
	s_setprio 0
	s_waitcnt lgkmcnt(0)
	s_barrier
	ds_read_b128 v[78:81], v22 offset:32768
	ds_read_b128 v[92:95], v22 offset:34816
	ds_read_b128 v[104:107], v23 offset:49152
	ds_read_b128 v[124:127], v23 offset:51200
	ds_read_b128 v[148:151], v22 offset:36864
	ds_read_b128 v[152:155], v22 offset:38912
	ds_read_b128 v[156:159], v23 offset:53248
	ds_read_b128 v[160:163], v23 offset:55296
	s_setprio 2
	global_load_dwordx4 v[168:171], v24, s[36:37] offset:384
	s_waitcnt vmcnt(8)
	ds_write_b128 v19, v[100:103]
	ds_read_b128 v[100:103], v20 offset:32768
	ds_read_b128 v[172:175], v21 offset:49152
	s_waitcnt lgkmcnt(8)
	v_mfma_f32_16x16x32_bf16 v[42:45], v[104:107], v[78:81], v[42:45]
	s_waitcnt lgkmcnt(3)
	v_mfma_f32_16x16x32_bf16 v[26:29], v[160:163], v[78:81], v[26:29]
	v_mfma_f32_16x16x32_bf16 v[108:111], v[124:127], v[78:81], v[108:111]
	v_mfma_f32_16x16x32_bf16 v[112:115], v[156:159], v[78:81], v[112:115]
	global_load_dwordx4 v[78:81], v245, s[36:37] offset:384
	v_mfma_f32_16x16x32_bf16 v[46:49], v[104:107], v[92:95], v[46:49]
	s_waitcnt vmcnt(8)
	ds_write_b128 v19, v[120:123] offset:4096
	v_mfma_f32_16x16x32_bf16 v[30:33], v[160:163], v[92:95], v[30:33]
	ds_read_b128 v[120:123], v20 offset:34816
	v_mfma_f32_16x16x32_bf16 v[116:119], v[124:127], v[92:95], v[116:119]
	ds_read_b128 v[176:179], v21 offset:51200
	v_mfma_f32_16x16x32_bf16 v[132:135], v[156:159], v[92:95], v[132:135]
	global_load_dwordx4 v[92:95], v246, s[36:37] offset:384
	v_mfma_f32_16x16x32_bf16 v[50:53], v[104:107], v[148:151], v[50:53]
	s_waitcnt vmcnt(8)
	ds_write_b128 v19, v[144:147] offset:8192
	v_mfma_f32_16x16x32_bf16 v[34:37], v[160:163], v[148:151], v[34:37]
	ds_read_b128 v[144:147], v20 offset:36864
	v_mfma_f32_16x16x32_bf16 v[136:139], v[124:127], v[148:151], v[136:139]
	ds_read_b128 v[180:183], v21 offset:53248
	v_mfma_f32_16x16x32_bf16 v[140:143], v[156:159], v[148:151], v[140:143]
	global_load_dwordx4 v[148:151], v247, s[36:37] offset:384
	v_mfma_f32_16x16x32_bf16 v[54:57], v[104:107], v[152:155], v[54:57]
	s_waitcnt vmcnt(8)
	ds_write_b128 v19, v[164:167] offset:12288
	v_mfma_f32_16x16x32_bf16 v[66:69], v[124:127], v[152:155], v[66:69]
	ds_read_b128 v[164:167], v20 offset:38912
	v_mfma_f32_16x16x32_bf16 v[70:73], v[156:159], v[152:155], v[70:73]
	ds_read_b128 v[184:187], v21 offset:55296
	v_mfma_f32_16x16x32_bf16 v[38:41], v[160:163], v[152:155], v[38:41]
	global_load_dwordx4 v[104:107], v18, s[6:7] offset:384
	s_waitcnt vmcnt(8)
	ds_write_b128 v19, v[96:99] offset:16384
	s_waitcnt lgkmcnt(10)
	v_mfma_f32_16x16x32_bf16 v[42:45], v[172:175], v[100:103], v[42:45]
	s_waitcnt lgkmcnt(1)
	v_mfma_f32_16x16x32_bf16 v[26:29], v[184:187], v[100:103], v[26:29]
	v_mfma_f32_16x16x32_bf16 v[96:99], v[176:179], v[100:103], v[108:111]
	v_mfma_f32_16x16x32_bf16 v[108:111], v[180:183], v[100:103], v[112:115]
	global_load_dwordx4 v[100:103], v248, s[6:7] offset:384
	s_waitcnt vmcnt(8)
	ds_write_b128 v19, v[58:61] offset:20480
	v_mfma_f32_16x16x32_bf16 v[46:49], v[172:175], v[120:123], v[46:49]
	v_mfma_f32_16x16x32_bf16 v[58:61], v[176:179], v[120:123], v[116:119]
	v_mfma_f32_16x16x32_bf16 v[30:33], v[184:187], v[120:123], v[30:33]
	v_mfma_f32_16x16x32_bf16 v[112:115], v[180:183], v[120:123], v[132:135]
	global_load_dwordx4 v[116:119], v249, s[6:7] offset:384
	s_waitcnt vmcnt(8)
	ds_write_b128 v19, v[62:65] offset:24576
	v_mfma_f32_16x16x32_bf16 v[50:53], v[172:175], v[144:147], v[50:53]
	v_mfma_f32_16x16x32_bf16 v[62:65], v[176:179], v[144:147], v[136:139]
	v_mfma_f32_16x16x32_bf16 v[34:37], v[184:187], v[144:147], v[34:37]
	v_mfma_f32_16x16x32_bf16 v[120:123], v[180:183], v[144:147], v[140:143]
	global_load_dwordx4 v[124:127], v250, s[6:7] offset:384
	v_mfma_f32_16x16x32_bf16 v[54:57], v[172:175], v[164:167], v[54:57]
	s_waitcnt vmcnt(8)
	ds_write_b128 v19, v[74:77] offset:28672
	v_mfma_f32_16x16x32_bf16 v[66:69], v[176:179], v[164:167], v[66:69]
	v_mfma_f32_16x16x32_bf16 v[70:73], v[180:183], v[164:167], v[70:73]
	v_mfma_f32_16x16x32_bf16 v[38:41], v[184:187], v[164:167], v[38:41]
	s_setprio 0
	s_waitcnt lgkmcnt(0)
	s_barrier
; template <int MODE>
; __device__ __forceinline__ void gemm_tile(const Params& P, int tm, int tn, unsigned char* smem) {
;     ...
; #pragma unroll
;         for (int i = 0; i < 4; ++i) { fa[i] = *(const bf16x8*)(sA + arow_off + i * 2048 + ch0); fb[i] = *(const bf16x8*)(sB + brow_off + i * 2048 + ch0); }
;         __builtin_amdgcn_sched_barrier(0);
;         __builtin_amdgcn_s_setprio(2);
;         if (wr_ok) *(uint4*)(nA + soff0) = ra0;
;         if (ld_ok) ra0 = *(const uint4*)(Ab + (aoff + 0u * LDA + koa));
;         ga[0] = *(const bf16x8*)(sA + arow_off + 0 * 2048 + ch1); gb[0] = *(const bf16x8*)(sB + brow_off + 0 * 2048 + ch1);
;         __builtin_amdgcn_sched_barrier(0);
; #pragma unroll
;         for (int j = 0; j < 4; ++j) acc[0][j] = __builtin_amdgcn_mfma_f32_16x16x32_bf16(fb[j], fa[0], acc[0][j], 0, 0, 0);
;         __builtin_amdgcn_sched_barrier(0);
;         if (wr_ok) *(uint4*)(nA + soff0 + 4096) = ra1;
;         if (ld_ok) ra1 = *(const uint4*)(Ab + (aoff + 32u * LDA + koa));
;         ga[1] = *(const bf16x8*)(sA + arow_off + 1 * 2048 + ch1); gb[1] = *(const bf16x8*)(sB + brow_off + 1 * 2048 + ch1);
;         __builtin_amdgcn_sched_barrier(0);
; #pragma unroll
;         for (int j = 0; j < 4; ++j) acc[1][j] = __builtin_amdgcn_mfma_f32_16x16x32_bf16(fb[j], fa[1], acc[1][j], 0, 0, 0);
;         __builtin_amdgcn_sched_barrier(0);
;         if (wr_ok) *(uint4*)(nA + soff0 + 8192) = ra2;
;         if (ld_ok) ra2 = *(const uint4*)(Ab + (aoff + 64u * LDA + koa));
;         ga[2] = *(const bf16x8*)(sA + arow_off + 2 * 2048 + ch1); gb[2] = *(const bf16x8*)(sB + brow_off + 2 * 2048 + ch1);
;         __builtin_amdgcn_sched_barrier(0);
; #pragma unroll
;         for (int j = 0; j < 4; ++j) acc[2][j] = __builtin_amdgcn_mfma_f32_16x16x32_bf16(fb[j], fa[2], acc[2][j], 0, 0, 0);
;         __builtin_amdgcn_sched_barrier(0);
;         if (wr_ok) *(uint4*)(nA + soff0 + 12288) = ra3;
;         if (ld_ok) ra3 = *(const uint4*)(Ab + (aoff + 96u * LDA + koa));
;         ga[3] = *(const bf16x8*)(sA + arow_off + 3 * 2048 + ch1); gb[3] = *(const bf16x8*)(sB + brow_off + 3 * 2048 + ch1);
;         __builtin_amdgcn_sched_barrier(0);
; #pragma unroll
;         for (int j = 0; j < 4; ++j) acc[3][j] = __builtin_amdgcn_mfma_f32_16x16x32_bf16(fb[j], fa[3], acc[3][j], 0, 0, 0);
;         __builtin_amdgcn_sched_barrier(0);
;         if (wr_ok) *(uint4*)(nB + soff0) = rb0;
	ds_read_b128 v[74:77], v22
	ds_read_b128 v[132:135], v22 offset:2048
	ds_read_b128 v[136:139], v23 offset:16384
	ds_read_b128 v[140:143], v23 offset:18432
	ds_read_b128 v[144:147], v22 offset:4096
	ds_read_b128 v[152:155], v22 offset:6144
	ds_read_b128 v[156:159], v23 offset:20480
	ds_read_b128 v[160:163], v23 offset:22528
	s_setprio 2
	global_load_dwordx4 v[164:167], v24, s[36:37] offset:512
	s_waitcnt vmcnt(8)
	ds_write_b128 v19, v[168:171] offset:32768
	ds_read_b128 v[168:171], v20
	ds_read_b128 v[172:175], v21 offset:16384
	s_waitcnt lgkmcnt(8)
	v_mfma_f32_16x16x32_bf16 v[42:45], v[136:139], v[74:77], v[42:45]
	s_waitcnt lgkmcnt(3)
	v_mfma_f32_16x16x32_bf16 v[26:29], v[160:163], v[74:77], v[26:29]
	v_mfma_f32_16x16x32_bf16 v[96:99], v[140:143], v[74:77], v[96:99]
	v_mfma_f32_16x16x32_bf16 v[108:111], v[156:159], v[74:77], v[108:111]
	global_load_dwordx4 v[74:77], v245, s[36:37] offset:512
	v_mfma_f32_16x16x32_bf16 v[46:49], v[136:139], v[132:135], v[46:49]
	s_waitcnt vmcnt(8)
	ds_write_b128 v19, v[78:81] offset:36864
	v_mfma_f32_16x16x32_bf16 v[58:61], v[140:143], v[132:135], v[58:61]
	ds_read_b128 v[78:81], v20 offset:2048
	v_mfma_f32_16x16x32_bf16 v[30:33], v[160:163], v[132:135], v[30:33]
	ds_read_b128 v[176:179], v21 offset:18432
	v_mfma_f32_16x16x32_bf16 v[112:115], v[156:159], v[132:135], v[112:115]
	global_load_dwordx4 v[132:135], v246, s[36:37] offset:512
	v_mfma_f32_16x16x32_bf16 v[50:53], v[136:139], v[144:147], v[50:53]
	s_waitcnt vmcnt(8)
	ds_write_b128 v19, v[92:95] offset:40960
	v_mfma_f32_16x16x32_bf16 v[62:65], v[140:143], v[144:147], v[62:65]
	ds_read_b128 v[92:95], v20 offset:4096
	v_mfma_f32_16x16x32_bf16 v[34:37], v[160:163], v[144:147], v[34:37]
	ds_read_b128 v[180:183], v21 offset:20480
	v_mfma_f32_16x16x32_bf16 v[120:123], v[156:159], v[144:147], v[120:123]
	global_load_dwordx4 v[144:147], v247, s[36:37] offset:512
	v_mfma_f32_16x16x32_bf16 v[54:57], v[136:139], v[152:155], v[54:57]
	s_waitcnt vmcnt(8)
	ds_write_b128 v19, v[148:151] offset:45056
	v_mfma_f32_16x16x32_bf16 v[66:69], v[140:143], v[152:155], v[66:69]
	ds_read_b128 v[148:151], v20 offset:6144
	v_mfma_f32_16x16x32_bf16 v[70:73], v[156:159], v[152:155], v[70:73]
	ds_read_b128 v[184:187], v21 offset:22528
	v_mfma_f32_16x16x32_bf16 v[38:41], v[160:163], v[152:155], v[38:41]
	global_load_dwordx4 v[136:139], v18, s[6:7] offset:512
	s_waitcnt vmcnt(8)
	ds_write_b128 v19, v[104:107] offset:49152
	s_waitcnt lgkmcnt(10)
	v_mfma_f32_16x16x32_bf16 v[42:45], v[172:175], v[168:171], v[42:45]
	s_waitcnt lgkmcnt(1)
	v_mfma_f32_16x16x32_bf16 v[26:29], v[184:187], v[168:171], v[26:29]
	v_mfma_f32_16x16x32_bf16 v[96:99], v[176:179], v[168:171], v[96:99]
	v_mfma_f32_16x16x32_bf16 v[104:107], v[180:183], v[168:171], v[108:111]
	global_load_dwordx4 v[108:111], v248, s[6:7] offset:512
	s_waitcnt vmcnt(8)
	ds_write_b128 v19, v[100:103] offset:53248
	v_mfma_f32_16x16x32_bf16 v[46:49], v[172:175], v[78:81], v[46:49]
	v_mfma_f32_16x16x32_bf16 v[58:61], v[176:179], v[78:81], v[58:61]
	v_mfma_f32_16x16x32_bf16 v[30:33], v[184:187], v[78:81], v[30:33]
	v_mfma_f32_16x16x32_bf16 v[100:103], v[180:183], v[78:81], v[112:115]
	global_load_dwordx4 v[78:81], v249, s[6:7] offset:512
	v_mfma_f32_16x16x32_bf16 v[50:53], v[172:175], v[92:95], v[50:53]
	s_waitcnt vmcnt(8)
	ds_write_b128 v19, v[116:119] offset:57344
	v_mfma_f32_16x16x32_bf16 v[62:65], v[176:179], v[92:95], v[62:65]
	v_mfma_f32_16x16x32_bf16 v[34:37], v[184:187], v[92:95], v[34:37]
	v_mfma_f32_16x16x32_bf16 v[112:115], v[180:183], v[92:95], v[120:123]
	global_load_dwordx4 v[92:95], v250, s[6:7] offset:512
	v_mfma_f32_16x16x32_bf16 v[54:57], v[172:175], v[148:151], v[54:57]
	s_waitcnt vmcnt(8)
	ds_write_b128 v19, v[124:127] offset:61440
	v_mfma_f32_16x16x32_bf16 v[66:69], v[176:179], v[148:151], v[66:69]
	v_mfma_f32_16x16x32_bf16 v[70:73], v[180:183], v[148:151], v[70:73]
	v_mfma_f32_16x16x32_bf16 v[38:41], v[184:187], v[148:151], v[38:41]
	s_setprio 0
	s_waitcnt lgkmcnt(0)
	s_barrier
	ds_read_b128 v[116:119], v22 offset:32768
	ds_read_b128 v[120:123], v22 offset:34816
	ds_read_b128 v[124:127], v23 offset:49152
	ds_read_b128 v[140:143], v23 offset:51200
	ds_read_b128 v[148:151], v22 offset:36864
	ds_read_b128 v[152:155], v22 offset:38912
	ds_read_b128 v[156:159], v23 offset:53248
	ds_read_b128 v[160:163], v23 offset:55296
	s_setprio 2
	global_load_dwordx4 v[168:171], v24, s[36:37] offset:640
	s_waitcnt vmcnt(8)
	ds_write_b128 v19, v[164:167]
	ds_read_b128 v[164:167], v20 offset:32768
	ds_read_b128 v[172:175], v21 offset:49152
	s_waitcnt lgkmcnt(8)
	v_mfma_f32_16x16x32_bf16 v[42:45], v[124:127], v[116:119], v[42:45]
	s_waitcnt lgkmcnt(3)
	v_mfma_f32_16x16x32_bf16 v[26:29], v[160:163], v[116:119], v[26:29]
	v_mfma_f32_16x16x32_bf16 v[96:99], v[140:143], v[116:119], v[96:99]
	v_mfma_f32_16x16x32_bf16 v[104:107], v[156:159], v[116:119], v[104:107]
	global_load_dwordx4 v[116:119], v245, s[36:37] offset:640
	v_mfma_f32_16x16x32_bf16 v[46:49], v[124:127], v[120:123], v[46:49]
	s_waitcnt vmcnt(8)
	ds_write_b128 v19, v[74:77] offset:4096
	v_mfma_f32_16x16x32_bf16 v[58:61], v[140:143], v[120:123], v[58:61]
	ds_read_b128 v[74:77], v20 offset:34816
	v_mfma_f32_16x16x32_bf16 v[30:33], v[160:163], v[120:123], v[30:33]
	ds_read_b128 v[176:179], v21 offset:51200
	v_mfma_f32_16x16x32_bf16 v[100:103], v[156:159], v[120:123], v[100:103]
	global_load_dwordx4 v[120:123], v246, s[36:37] offset:640
	v_mfma_f32_16x16x32_bf16 v[50:53], v[124:127], v[148:151], v[50:53]
	s_waitcnt vmcnt(8)
; template <int MODE>
; __device__ __forceinline__ void gemm_tile(const Params& P, int tm, int tn, unsigned char* smem) {
;     ...
; #pragma unroll
;         for (int i = 0; i < 4; ++i) { fa[i] = *(const bf16x8*)(sA + arow_off + i * 2048 + ch0); fb[i] = *(const bf16x8*)(sB + brow_off + i * 2048 + ch0); }
;         __builtin_amdgcn_sched_barrier(0);
;         __builtin_amdgcn_s_setprio(2);
;         if (wr_ok) *(uint4*)(nA + soff0) = ra0;
;         if (ld_ok) ra0 = *(const uint4*)(Ab + (aoff + 0u * LDA + koa));
;         ga[0] = *(const bf16x8*)(sA + arow_off + 0 * 2048 + ch1); gb[0] = *(const bf16x8*)(sB + brow_off + 0 * 2048 + ch1);
;         __builtin_amdgcn_sched_barrier(0);
; #pragma unroll
;         for (int j = 0; j < 4; ++j) acc[0][j] = __builtin_amdgcn_mfma_f32_16x16x32_bf16(fb[j], fa[0], acc[0][j], 0, 0, 0);
;         __builtin_amdgcn_sched_barrier(0);
;         if (wr_ok) *(uint4*)(nA + soff0 + 4096) = ra1;
;         if (ld_ok) ra1 = *(const uint4*)(Ab + (aoff + 32u * LDA + koa));
;         ga[1] = *(const bf16x8*)(sA + arow_off + 1 * 2048 + ch1); gb[1] = *(const bf16x8*)(sB + brow_off + 1 * 2048 + ch1);
;         __builtin_amdgcn_sched_barrier(0);
; #pragma unroll
;         for (int j = 0; j < 4; ++j) acc[1][j] = __builtin_amdgcn_mfma_f32_16x16x32_bf16(fb[j], fa[1], acc[1][j], 0, 0, 0);
;         __builtin_amdgcn_sched_barrier(0);
;         if (wr_ok) *(uint4*)(nA + soff0 + 8192) = ra2;
;         if (ld_ok) ra2 = *(const uint4*)(Ab + (aoff + 64u * LDA + koa));
;         ga[2] = *(const bf16x8*)(sA + arow_off + 2 * 2048 + ch1); gb[2] = *(const bf16x8*)(sB + brow_off + 2 * 2048 + ch1);
;         __builtin_amdgcn_sched_barrier(0);
; #pragma unroll
;         for (int j = 0; j < 4; ++j) acc[2][j] = __builtin_amdgcn_mfma_f32_16x16x32_bf16(fb[j], fa[2], acc[2][j], 0, 0, 0);
;         __builtin_amdgcn_sched_barrier(0);
;         if (wr_ok) *(uint4*)(nA + soff0 + 12288) = ra3;
;         if (ld_ok) ra3 = *(const uint4*)(Ab + (aoff + 96u * LDA + koa));
;         ga[3] = *(const bf16x8*)(sA + arow_off + 3 * 2048 + ch1); gb[3] = *(const bf16x8*)(sB + brow_off + 3 * 2048 + ch1);
;         __builtin_amdgcn_sched_barrier(0);
; #pragma unroll
;         for (int j = 0; j < 4; ++j) acc[3][j] = __builtin_amdgcn_mfma_f32_16x16x32_bf16(fb[j], fa[3], acc[3][j], 0, 0, 0);
;         __builtin_amdgcn_sched_barrier(0);
;         if (wr_ok) *(uint4*)(nB + soff0) = rb0;
	ds_write_b128 v19, v[132:135] offset:8192
	v_mfma_f32_16x16x32_bf16 v[62:65], v[140:143], v[148:151], v[62:65]
	ds_read_b128 v[132:135], v20 offset:36864
	v_mfma_f32_16x16x32_bf16 v[34:37], v[160:163], v[148:151], v[34:37]
	ds_read_b128 v[180:183], v21 offset:53248
	v_mfma_f32_16x16x32_bf16 v[112:115], v[156:159], v[148:151], v[112:115]
	global_load_dwordx4 v[148:151], v247, s[36:37] offset:640
	v_mfma_f32_16x16x32_bf16 v[54:57], v[124:127], v[152:155], v[54:57]
	s_waitcnt vmcnt(8)
	ds_write_b128 v19, v[144:147] offset:12288
	v_mfma_f32_16x16x32_bf16 v[66:69], v[140:143], v[152:155], v[66:69]
	ds_read_b128 v[144:147], v20 offset:38912
	v_mfma_f32_16x16x32_bf16 v[70:73], v[156:159], v[152:155], v[70:73]
	ds_read_b128 v[184:187], v21 offset:55296
	v_mfma_f32_16x16x32_bf16 v[38:41], v[160:163], v[152:155], v[38:41]
	global_load_dwordx4 v[124:127], v18, s[6:7] offset:640
	s_waitcnt vmcnt(8)
	ds_write_b128 v19, v[136:139] offset:16384
	s_waitcnt lgkmcnt(10)
	v_mfma_f32_16x16x32_bf16 v[42:45], v[172:175], v[164:167], v[42:45]
	s_waitcnt lgkmcnt(1)
	v_mfma_f32_16x16x32_bf16 v[26:29], v[184:187], v[164:167], v[26:29]
	v_mfma_f32_16x16x32_bf16 v[96:99], v[176:179], v[164:167], v[96:99]
	v_mfma_f32_16x16x32_bf16 v[104:107], v[180:183], v[164:167], v[104:107]
	global_load_dwordx4 v[136:139], v248, s[6:7] offset:640
	v_mfma_f32_16x16x32_bf16 v[46:49], v[172:175], v[74:77], v[46:49]
	s_waitcnt vmcnt(8)
	ds_write_b128 v19, v[108:111] offset:20480
	v_mfma_f32_16x16x32_bf16 v[58:61], v[176:179], v[74:77], v[58:61]
	v_mfma_f32_16x16x32_bf16 v[30:33], v[184:187], v[74:77], v[30:33]
	v_mfma_f32_16x16x32_bf16 v[100:103], v[180:183], v[74:77], v[100:103]
	global_load_dwordx4 v[74:77], v249, s[6:7] offset:640
	s_waitcnt vmcnt(8)
	ds_write_b128 v19, v[78:81] offset:24576
	v_mfma_f32_16x16x32_bf16 v[50:53], v[172:175], v[132:135], v[50:53]
	v_mfma_f32_16x16x32_bf16 v[62:65], v[176:179], v[132:135], v[62:65]
	v_mfma_f32_16x16x32_bf16 v[78:81], v[180:183], v[132:135], v[112:115]
	v_mfma_f32_16x16x32_bf16 v[34:37], v[184:187], v[132:135], v[34:37]
	global_load_dwordx4 v[108:111], v250, s[6:7] offset:640
	v_mfma_f32_16x16x32_bf16 v[54:57], v[172:175], v[144:147], v[54:57]
	s_waitcnt vmcnt(8)
	ds_write_b128 v19, v[92:95] offset:28672
	v_mfma_f32_16x16x32_bf16 v[66:69], v[176:179], v[144:147], v[66:69]
	v_mfma_f32_16x16x32_bf16 v[70:73], v[180:183], v[144:147], v[70:73]
	v_mfma_f32_16x16x32_bf16 v[38:41], v[184:187], v[144:147], v[38:41]
	s_setprio 0
	s_waitcnt lgkmcnt(0)
	s_barrier
	ds_read_b128 v[92:95], v22
	ds_read_b128 v[112:115], v22 offset:2048
	ds_read_b128 v[132:135], v23 offset:16384
	ds_read_b128 v[140:143], v23 offset:18432
	ds_read_b128 v[144:147], v22 offset:4096
	ds_read_b128 v[152:155], v22 offset:6144
	ds_read_b128 v[156:159], v23 offset:20480
	ds_read_b128 v[160:163], v23 offset:22528
	s_setprio 2
	global_load_dwordx4 v[164:167], v24, s[36:37] offset:768
	s_waitcnt vmcnt(8)
	ds_write_b128 v19, v[168:171] offset:32768
	ds_read_b128 v[168:171], v20
	ds_read_b128 v[172:175], v21 offset:16384
	s_waitcnt lgkmcnt(8)
	v_mfma_f32_16x16x32_bf16 v[42:45], v[132:135], v[92:95], v[42:45]
	s_waitcnt lgkmcnt(3)
	v_mfma_f32_16x16x32_bf16 v[26:29], v[160:163], v[92:95], v[26:29]
	v_mfma_f32_16x16x32_bf16 v[96:99], v[140:143], v[92:95], v[96:99]
	v_mfma_f32_16x16x32_bf16 v[104:107], v[156:159], v[92:95], v[104:107]
	global_load_dwordx4 v[92:95], v245, s[36:37] offset:768
	v_mfma_f32_16x16x32_bf16 v[46:49], v[132:135], v[112:115], v[46:49]
	s_waitcnt vmcnt(8)
	ds_write_b128 v19, v[116:119] offset:36864
	v_mfma_f32_16x16x32_bf16 v[58:61], v[140:143], v[112:115], v[58:61]
	ds_read_b128 v[116:119], v20 offset:2048
	v_mfma_f32_16x16x32_bf16 v[30:33], v[160:163], v[112:115], v[30:33]
	ds_read_b128 v[176:179], v21 offset:18432
	v_mfma_f32_16x16x32_bf16 v[100:103], v[156:159], v[112:115], v[100:103]
	global_load_dwordx4 v[112:115], v246, s[36:37] offset:768
	v_mfma_f32_16x16x32_bf16 v[50:53], v[132:135], v[144:147], v[50:53]
	s_waitcnt vmcnt(8)
	ds_write_b128 v19, v[120:123] offset:40960
	v_mfma_f32_16x16x32_bf16 v[62:65], v[140:143], v[144:147], v[62:65]
	ds_read_b128 v[120:123], v20 offset:4096
	v_mfma_f32_16x16x32_bf16 v[78:81], v[156:159], v[144:147], v[78:81]
	ds_read_b128 v[180:183], v21 offset:20480
	v_mfma_f32_16x16x32_bf16 v[34:37], v[160:163], v[144:147], v[34:37]
	global_load_dwordx4 v[144:147], v247, s[36:37] offset:768
	v_mfma_f32_16x16x32_bf16 v[54:57], v[132:135], v[152:155], v[54:57]
	s_waitcnt vmcnt(8)
	ds_write_b128 v19, v[148:151] offset:45056
	v_mfma_f32_16x16x32_bf16 v[66:69], v[140:143], v[152:155], v[66:69]
	ds_read_b128 v[148:151], v20 offset:6144
	v_mfma_f32_16x16x32_bf16 v[70:73], v[156:159], v[152:155], v[70:73]
	ds_read_b128 v[184:187], v21 offset:22528
	v_mfma_f32_16x16x32_bf16 v[38:41], v[160:163], v[152:155], v[38:41]
	global_load_dwordx4 v[132:135], v18, s[6:7] offset:768
	s_waitcnt vmcnt(8)
	ds_write_b128 v19, v[124:127] offset:49152
	s_waitcnt lgkmcnt(10)
	v_mfma_f32_16x16x32_bf16 v[42:45], v[172:175], v[168:171], v[42:45]
	s_waitcnt lgkmcnt(1)
	v_mfma_f32_16x16x32_bf16 v[26:29], v[184:187], v[168:171], v[26:29]
	v_mfma_f32_16x16x32_bf16 v[96:99], v[176:179], v[168:171], v[96:99]
	v_mfma_f32_16x16x32_bf16 v[104:107], v[180:183], v[168:171], v[104:107]
	global_load_dwordx4 v[124:127], v248, s[6:7] offset:768
	v_mfma_f32_16x16x32_bf16 v[46:49], v[172:175], v[116:119], v[46:49]
	s_waitcnt vmcnt(8)
	ds_write_b128 v19, v[136:139] offset:53248
	v_mfma_f32_16x16x32_bf16 v[58:61], v[176:179], v[116:119], v[58:61]
	v_mfma_f32_16x16x32_bf16 v[30:33], v[184:187], v[116:119], v[30:33]
	v_mfma_f32_16x16x32_bf16 v[100:103], v[180:183], v[116:119], v[100:103]
	global_load_dwordx4 v[116:119], v249, s[6:7] offset:768
	s_waitcnt vmcnt(8)
	ds_write_b128 v19, v[74:77] offset:57344
	v_mfma_f32_16x16x32_bf16 v[50:53], v[172:175], v[120:123], v[50:53]
	v_mfma_f32_16x16x32_bf16 v[62:65], v[176:179], v[120:123], v[62:65]
	v_mfma_f32_16x16x32_bf16 v[74:77], v[180:183], v[120:123], v[78:81]
	v_mfma_f32_16x16x32_bf16 v[34:37], v[184:187], v[120:123], v[34:37]
	global_load_dwordx4 v[78:81], v250, s[6:7] offset:768
	v_mfma_f32_16x16x32_bf16 v[54:57], v[172:175], v[148:151], v[54:57]
	s_waitcnt vmcnt(8)
	ds_write_b128 v19, v[108:111] offset:61440
	v_mfma_f32_16x16x32_bf16 v[66:69], v[176:179], v[148:151], v[66:69]
	v_mfma_f32_16x16x32_bf16 v[70:73], v[180:183], v[148:151], v[70:73]
	v_mfma_f32_16x16x32_bf16 v[38:41], v[184:187], v[148:151], v[38:41]
	s_setprio 0
	s_waitcnt lgkmcnt(0)
	s_barrier
; template <int MODE>
; __device__ __forceinline__ void gemm_tile(const Params& P, int tm, int tn, unsigned char* smem) {
;     ...
; #pragma unroll
;         for (int i = 0; i < 4; ++i) { fa[i] = *(const bf16x8*)(sA + arow_off + i * 2048 + ch0); fb[i] = *(const bf16x8*)(sB + brow_off + i * 2048 + ch0); }
;         __builtin_amdgcn_sched_barrier(0);
;         __builtin_amdgcn_s_setprio(2);
;         if (wr_ok) *(uint4*)(nA + soff0) = ra0;
;         if (ld_ok) ra0 = *(const uint4*)(Ab + (aoff + 0u * LDA + koa));
;         ga[0] = *(const bf16x8*)(sA + arow_off + 0 * 2048 + ch1); gb[0] = *(const bf16x8*)(sB + brow_off + 0 * 2048 + ch1);
;         __builtin_amdgcn_sched_barrier(0);
; #pragma unroll
;         for (int j = 0; j < 4; ++j) acc[0][j] = __builtin_amdgcn_mfma_f32_16x16x32_bf16(fb[j], fa[0], acc[0][j], 0, 0, 0);
;         __builtin_amdgcn_sched_barrier(0);
;         if (wr_ok) *(uint4*)(nA + soff0 + 4096) = ra1;
;         if (ld_ok) ra1 = *(const uint4*)(Ab + (aoff + 32u * LDA + koa));
;         ga[1] = *(const bf16x8*)(sA + arow_off + 1 * 2048 + ch1); gb[1] = *(const bf16x8*)(sB + brow_off + 1 * 2048 + ch1);
;         __builtin_amdgcn_sched_barrier(0);
; #pragma unroll
;         for (int j = 0; j < 4; ++j) acc[1][j] = __builtin_amdgcn_mfma_f32_16x16x32_bf16(fb[j], fa[1], acc[1][j], 0, 0, 0);
;         __builtin_amdgcn_sched_barrier(0);
;         if (wr_ok) *(uint4*)(nA + soff0 + 8192) = ra2;
;         if (ld_ok) ra2 = *(const uint4*)(Ab + (aoff + 64u * LDA + koa));
;         ga[2] = *(const bf16x8*)(sA + arow_off + 2 * 2048 + ch1); gb[2] = *(const bf16x8*)(sB + brow_off + 2 * 2048 + ch1);
;         __builtin_amdgcn_sched_barrier(0);
; #pragma unroll
;         for (int j = 0; j < 4; ++j) acc[2][j] = __builtin_amdgcn_mfma_f32_16x16x32_bf16(fb[j], fa[2], acc[2][j], 0, 0, 0);
;         __builtin_amdgcn_sched_barrier(0);
;         if (wr_ok) *(uint4*)(nA + soff0 + 12288) = ra3;
;         if (ld_ok) ra3 = *(const uint4*)(Ab + (aoff + 96u * LDA + koa));
;         ga[3] = *(const bf16x8*)(sA + arow_off + 3 * 2048 + ch1); gb[3] = *(const bf16x8*)(sB + brow_off + 3 * 2048 + ch1);
;         __builtin_amdgcn_sched_barrier(0);
; #pragma unroll
;         for (int j = 0; j < 4; ++j) acc[3][j] = __builtin_amdgcn_mfma_f32_16x16x32_bf16(fb[j], fa[3], acc[3][j], 0, 0, 0);
;         __builtin_amdgcn_sched_barrier(0);
;         if (wr_ok) *(uint4*)(nB + soff0) = rb0;
	ds_read_b128 v[108:111], v22 offset:32768
	ds_read_b128 v[120:123], v22 offset:34816
	ds_read_b128 v[136:139], v23 offset:49152
	ds_read_b128 v[140:143], v23 offset:51200
	ds_read_b128 v[148:151], v22 offset:36864
	ds_read_b128 v[152:155], v22 offset:38912
	ds_read_b128 v[156:159], v23 offset:53248
	ds_read_b128 v[160:163], v23 offset:55296
	s_setprio 2
	global_load_dwordx4 v[168:171], v24, s[36:37] offset:896
	s_waitcnt vmcnt(8)
	ds_write_b128 v19, v[164:167]
	ds_read_b128 v[164:167], v20 offset:32768
	ds_read_b128 v[172:175], v21 offset:49152
	s_waitcnt lgkmcnt(8)
	v_mfma_f32_16x16x32_bf16 v[42:45], v[136:139], v[108:111], v[42:45]
	s_waitcnt lgkmcnt(3)
	v_mfma_f32_16x16x32_bf16 v[26:29], v[160:163], v[108:111], v[26:29]
	v_mfma_f32_16x16x32_bf16 v[96:99], v[140:143], v[108:111], v[96:99]
	v_mfma_f32_16x16x32_bf16 v[104:107], v[156:159], v[108:111], v[104:107]
	global_load_dwordx4 v[108:111], v245, s[36:37] offset:896
	v_mfma_f32_16x16x32_bf16 v[46:49], v[136:139], v[120:123], v[46:49]
	s_waitcnt vmcnt(8)
	ds_write_b128 v19, v[92:95] offset:4096
	v_mfma_f32_16x16x32_bf16 v[58:61], v[140:143], v[120:123], v[58:61]
	ds_read_b128 v[92:95], v20 offset:34816
	v_mfma_f32_16x16x32_bf16 v[30:33], v[160:163], v[120:123], v[30:33]
	ds_read_b128 v[176:179], v21 offset:51200
	v_mfma_f32_16x16x32_bf16 v[100:103], v[156:159], v[120:123], v[100:103]
	global_load_dwordx4 v[120:123], v246, s[36:37] offset:896
	v_mfma_f32_16x16x32_bf16 v[50:53], v[136:139], v[148:151], v[50:53]
	s_waitcnt vmcnt(8)
	ds_write_b128 v19, v[112:115] offset:8192
	v_mfma_f32_16x16x32_bf16 v[62:65], v[140:143], v[148:151], v[62:65]
	ds_read_b128 v[112:115], v20 offset:36864
	v_mfma_f32_16x16x32_bf16 v[74:77], v[156:159], v[148:151], v[74:77]
	ds_read_b128 v[180:183], v21 offset:53248
	v_mfma_f32_16x16x32_bf16 v[34:37], v[160:163], v[148:151], v[34:37]
	global_load_dwordx4 v[148:151], v247, s[36:37] offset:896
	v_mfma_f32_16x16x32_bf16 v[54:57], v[136:139], v[152:155], v[54:57]
	s_waitcnt vmcnt(8)
	ds_write_b128 v19, v[144:147] offset:12288
	v_mfma_f32_16x16x32_bf16 v[66:69], v[140:143], v[152:155], v[66:69]
	ds_read_b128 v[144:147], v20 offset:38912
	v_mfma_f32_16x16x32_bf16 v[70:73], v[156:159], v[152:155], v[70:73]
	ds_read_b128 v[184:187], v21 offset:55296
	v_mfma_f32_16x16x32_bf16 v[38:41], v[160:163], v[152:155], v[38:41]
	global_load_dwordx4 v[136:139], v18, s[6:7] offset:896
	s_waitcnt vmcnt(8)
	ds_write_b128 v19, v[132:135] offset:16384
	s_waitcnt lgkmcnt(10)
	v_mfma_f32_16x16x32_bf16 v[42:45], v[172:175], v[164:167], v[42:45]
	s_waitcnt lgkmcnt(1)
	v_mfma_f32_16x16x32_bf16 v[26:29], v[184:187], v[164:167], v[26:29]
	v_mfma_f32_16x16x32_bf16 v[96:99], v[176:179], v[164:167], v[96:99]
	v_mfma_f32_16x16x32_bf16 v[104:107], v[180:183], v[164:167], v[104:107]
	global_load_dwordx4 v[132:135], v248, s[6:7] offset:896
	v_mfma_f32_16x16x32_bf16 v[46:49], v[172:175], v[92:95], v[46:49]
	s_waitcnt vmcnt(8)
	ds_write_b128 v19, v[124:127] offset:20480
	v_mfma_f32_16x16x32_bf16 v[58:61], v[176:179], v[92:95], v[58:61]
	v_mfma_f32_16x16x32_bf16 v[30:33], v[184:187], v[92:95], v[30:33]
	v_mfma_f32_16x16x32_bf16 v[100:103], v[180:183], v[92:95], v[100:103]
	global_load_dwordx4 v[92:95], v249, s[6:7] offset:896
	v_mfma_f32_16x16x32_bf16 v[50:53], v[172:175], v[112:115], v[50:53]
	s_waitcnt vmcnt(8)
	ds_write_b128 v19, v[116:119] offset:24576
	v_mfma_f32_16x16x32_bf16 v[62:65], v[176:179], v[112:115], v[62:65]
	v_mfma_f32_16x16x32_bf16 v[74:77], v[180:183], v[112:115], v[74:77]
	v_mfma_f32_16x16x32_bf16 v[34:37], v[184:187], v[112:115], v[34:37]
	global_load_dwordx4 v[112:115], v250, s[6:7] offset:896
	v_mfma_f32_16x16x32_bf16 v[54:57], v[172:175], v[144:147], v[54:57]
	s_waitcnt vmcnt(8)
	ds_write_b128 v19, v[78:81] offset:28672
	v_mfma_f32_16x16x32_bf16 v[66:69], v[176:179], v[144:147], v[66:69]
	v_mfma_f32_16x16x32_bf16 v[70:73], v[180:183], v[144:147], v[70:73]
	v_mfma_f32_16x16x32_bf16 v[38:41], v[184:187], v[144:147], v[38:41]
	s_setprio 0
	s_waitcnt lgkmcnt(0)
	s_barrier
	ds_read_b128 v[78:81], v22
	ds_read_b128 v[116:119], v22 offset:2048
	ds_read_b128 v[124:127], v23 offset:16384
	ds_read_b128 v[140:143], v23 offset:18432
	ds_read_b128 v[144:147], v22 offset:4096
	ds_read_b128 v[152:155], v22 offset:6144
	ds_read_b128 v[156:159], v23 offset:20480
	ds_read_b128 v[160:163], v23 offset:22528
	s_setprio 2
	global_load_dwordx4 v[164:167], v24, s[36:37] offset:1024
	s_waitcnt vmcnt(8)
	ds_write_b128 v19, v[168:171] offset:32768
	ds_read_b128 v[168:171], v20
	ds_read_b128 v[172:175], v21 offset:16384
	s_waitcnt lgkmcnt(8)
	v_mfma_f32_16x16x32_bf16 v[42:45], v[124:127], v[78:81], v[42:45]
	s_waitcnt lgkmcnt(3)
	v_mfma_f32_16x16x32_bf16 v[26:29], v[160:163], v[78:81], v[26:29]
	v_mfma_f32_16x16x32_bf16 v[96:99], v[140:143], v[78:81], v[96:99]
	v_mfma_f32_16x16x32_bf16 v[104:107], v[156:159], v[78:81], v[104:107]
	global_load_dwordx4 v[78:81], v245, s[36:37] offset:1024
	v_mfma_f32_16x16x32_bf16 v[46:49], v[124:127], v[116:119], v[46:49]
	s_waitcnt vmcnt(8)
	ds_write_b128 v19, v[108:111] offset:36864
	v_mfma_f32_16x16x32_bf16 v[58:61], v[140:143], v[116:119], v[58:61]
	ds_read_b128 v[108:111], v20 offset:2048
	v_mfma_f32_16x16x32_bf16 v[30:33], v[160:163], v[116:119], v[30:33]
	ds_read_b128 v[176:179], v21 offset:18432
	v_mfma_f32_16x16x32_bf16 v[100:103], v[156:159], v[116:119], v[100:103]
	global_load_dwordx4 v[116:119], v246, s[36:37] offset:1024
	v_mfma_f32_16x16x32_bf16 v[50:53], v[124:127], v[144:147], v[50:53]
	s_waitcnt vmcnt(8)
; template <int MODE>
; __device__ __forceinline__ void gemm_tile(const Params& P, int tm, int tn, unsigned char* smem) {
;     ...
; #pragma unroll
;         for (int i = 0; i < 4; ++i) { fa[i] = *(const bf16x8*)(sA + arow_off + i * 2048 + ch0); fb[i] = *(const bf16x8*)(sB + brow_off + i * 2048 + ch0); }
;         __builtin_amdgcn_sched_barrier(0);
;         __builtin_amdgcn_s_setprio(2);
;         if (wr_ok) *(uint4*)(nA + soff0) = ra0;
;         if (ld_ok) ra0 = *(const uint4*)(Ab + (aoff + 0u * LDA + koa));
;         ga[0] = *(const bf16x8*)(sA + arow_off + 0 * 2048 + ch1); gb[0] = *(const bf16x8*)(sB + brow_off + 0 * 2048 + ch1);
;         __builtin_amdgcn_sched_barrier(0);
; #pragma unroll
;         for (int j = 0; j < 4; ++j) acc[0][j] = __builtin_amdgcn_mfma_f32_16x16x32_bf16(fb[j], fa[0], acc[0][j], 0, 0, 0);
;         __builtin_amdgcn_sched_barrier(0);
;         if (wr_ok) *(uint4*)(nA + soff0 + 4096) = ra1;
;         if (ld_ok) ra1 = *(const uint4*)(Ab + (aoff + 32u * LDA + koa));
;         ga[1] = *(const bf16x8*)(sA + arow_off + 1 * 2048 + ch1); gb[1] = *(const bf16x8*)(sB + brow_off + 1 * 2048 + ch1);
;         __builtin_amdgcn_sched_barrier(0);
; #pragma unroll
;         for (int j = 0; j < 4; ++j) acc[1][j] = __builtin_amdgcn_mfma_f32_16x16x32_bf16(fb[j], fa[1], acc[1][j], 0, 0, 0);
;         __builtin_amdgcn_sched_barrier(0);
;         if (wr_ok) *(uint4*)(nA + soff0 + 8192) = ra2;
;         if (ld_ok) ra2 = *(const uint4*)(Ab + (aoff + 64u * LDA + koa));
;         ga[2] = *(const bf16x8*)(sA + arow_off + 2 * 2048 + ch1); gb[2] = *(const bf16x8*)(sB + brow_off + 2 * 2048 + ch1);
;         __builtin_amdgcn_sched_barrier(0);
; #pragma unroll
;         for (int j = 0; j < 4; ++j) acc[2][j] = __builtin_amdgcn_mfma_f32_16x16x32_bf16(fb[j], fa[2], acc[2][j], 0, 0, 0);
;         __builtin_amdgcn_sched_barrier(0);
;         if (wr_ok) *(uint4*)(nA + soff0 + 12288) = ra3;
;         if (ld_ok) ra3 = *(const uint4*)(Ab + (aoff + 96u * LDA + koa));
;         ga[3] = *(const bf16x8*)(sA + arow_off + 3 * 2048 + ch1); gb[3] = *(const bf16x8*)(sB + brow_off + 3 * 2048 + ch1);
;         __builtin_amdgcn_sched_barrier(0);
; #pragma unroll
;         for (int j = 0; j < 4; ++j) acc[3][j] = __builtin_amdgcn_mfma_f32_16x16x32_bf16(fb[j], fa[3], acc[3][j], 0, 0, 0);
;         __builtin_amdgcn_sched_barrier(0);
;         if (wr_ok) *(uint4*)(nB + soff0) = rb0;
	ds_write_b128 v19, v[120:123] offset:40960
	v_mfma_f32_16x16x32_bf16 v[62:65], v[140:143], v[144:147], v[62:65]
	ds_read_b128 v[120:123], v20 offset:4096
	v_mfma_f32_16x16x32_bf16 v[74:77], v[156:159], v[144:147], v[74:77]
	ds_read_b128 v[180:183], v21 offset:20480
	v_mfma_f32_16x16x32_bf16 v[34:37], v[160:163], v[144:147], v[34:37]
	global_load_dwordx4 v[144:147], v247, s[36:37] offset:1024
	v_mfma_f32_16x16x32_bf16 v[54:57], v[124:127], v[152:155], v[54:57]
	s_waitcnt vmcnt(8)
	ds_write_b128 v19, v[148:151] offset:45056
	v_mfma_f32_16x16x32_bf16 v[66:69], v[140:143], v[152:155], v[66:69]
	ds_read_b128 v[148:151], v20 offset:6144
	v_mfma_f32_16x16x32_bf16 v[70:73], v[156:159], v[152:155], v[70:73]
	ds_read_b128 v[184:187], v21 offset:22528
	v_mfma_f32_16x16x32_bf16 v[38:41], v[160:163], v[152:155], v[38:41]
	global_load_dwordx4 v[124:127], v18, s[6:7] offset:1024
	s_waitcnt vmcnt(8)
	ds_write_b128 v19, v[136:139] offset:49152
	s_waitcnt lgkmcnt(10)
	v_mfma_f32_16x16x32_bf16 v[42:45], v[172:175], v[168:171], v[42:45]
	s_waitcnt lgkmcnt(1)
	v_mfma_f32_16x16x32_bf16 v[26:29], v[184:187], v[168:171], v[26:29]
	v_mfma_f32_16x16x32_bf16 v[96:99], v[176:179], v[168:171], v[96:99]
	v_mfma_f32_16x16x32_bf16 v[104:107], v[180:183], v[168:171], v[104:107]
	global_load_dwordx4 v[136:139], v248, s[6:7] offset:1024
	v_mfma_f32_16x16x32_bf16 v[46:49], v[172:175], v[108:111], v[46:49]
	s_waitcnt vmcnt(8)
	ds_write_b128 v19, v[132:135] offset:53248
	v_mfma_f32_16x16x32_bf16 v[58:61], v[176:179], v[108:111], v[58:61]
	v_mfma_f32_16x16x32_bf16 v[30:33], v[184:187], v[108:111], v[30:33]
	v_mfma_f32_16x16x32_bf16 v[100:103], v[180:183], v[108:111], v[100:103]
	global_load_dwordx4 v[108:111], v249, s[6:7] offset:1024
	v_mfma_f32_16x16x32_bf16 v[50:53], v[172:175], v[120:123], v[50:53]
	s_waitcnt vmcnt(8)
	ds_write_b128 v19, v[92:95] offset:57344
	v_mfma_f32_16x16x32_bf16 v[62:65], v[176:179], v[120:123], v[62:65]
	v_mfma_f32_16x16x32_bf16 v[74:77], v[180:183], v[120:123], v[74:77]
	v_mfma_f32_16x16x32_bf16 v[34:37], v[184:187], v[120:123], v[34:37]
	global_load_dwordx4 v[92:95], v250, s[6:7] offset:1024
	v_mfma_f32_16x16x32_bf16 v[54:57], v[172:175], v[148:151], v[54:57]
	s_waitcnt vmcnt(8)
	ds_write_b128 v19, v[112:115] offset:61440
	v_mfma_f32_16x16x32_bf16 v[66:69], v[176:179], v[148:151], v[66:69]
	v_mfma_f32_16x16x32_bf16 v[70:73], v[180:183], v[148:151], v[70:73]
	v_mfma_f32_16x16x32_bf16 v[38:41], v[184:187], v[148:151], v[38:41]
	s_setprio 0
	s_waitcnt lgkmcnt(0)
	s_barrier
	ds_read_b128 v[112:115], v22 offset:32768
	ds_read_b128 v[120:123], v22 offset:34816
	ds_read_b128 v[132:135], v23 offset:49152
	ds_read_b128 v[140:143], v23 offset:51200
	ds_read_b128 v[148:151], v22 offset:36864
	ds_read_b128 v[152:155], v22 offset:38912
	ds_read_b128 v[156:159], v23 offset:53248
	ds_read_b128 v[160:163], v23 offset:55296
	s_setprio 2
	global_load_dwordx4 v[168:171], v24, s[36:37] offset:1152
	s_waitcnt vmcnt(8)
	ds_write_b128 v19, v[164:167]
	ds_read_b128 v[164:167], v20 offset:32768
	ds_read_b128 v[172:175], v21 offset:49152
	s_waitcnt lgkmcnt(8)
	v_mfma_f32_16x16x32_bf16 v[42:45], v[132:135], v[112:115], v[42:45]
	s_waitcnt lgkmcnt(3)
	v_mfma_f32_16x16x32_bf16 v[26:29], v[160:163], v[112:115], v[26:29]
	v_mfma_f32_16x16x32_bf16 v[96:99], v[140:143], v[112:115], v[96:99]
	v_mfma_f32_16x16x32_bf16 v[104:107], v[156:159], v[112:115], v[104:107]
	global_load_dwordx4 v[112:115], v245, s[36:37] offset:1152
	v_mfma_f32_16x16x32_bf16 v[46:49], v[132:135], v[120:123], v[46:49]
	s_waitcnt vmcnt(8)
	ds_write_b128 v19, v[78:81] offset:4096
	v_mfma_f32_16x16x32_bf16 v[58:61], v[140:143], v[120:123], v[58:61]
	ds_read_b128 v[78:81], v20 offset:34816
	v_mfma_f32_16x16x32_bf16 v[30:33], v[160:163], v[120:123], v[30:33]
	ds_read_b128 v[176:179], v21 offset:51200
	v_mfma_f32_16x16x32_bf16 v[100:103], v[156:159], v[120:123], v[100:103]
	global_load_dwordx4 v[120:123], v246, s[36:37] offset:1152
	v_mfma_f32_16x16x32_bf16 v[50:53], v[132:135], v[148:151], v[50:53]
	s_waitcnt vmcnt(8)
	ds_write_b128 v19, v[116:119] offset:8192
	v_mfma_f32_16x16x32_bf16 v[62:65], v[140:143], v[148:151], v[62:65]
	ds_read_b128 v[116:119], v20 offset:36864
	v_mfma_f32_16x16x32_bf16 v[74:77], v[156:159], v[148:151], v[74:77]
	ds_read_b128 v[180:183], v21 offset:53248
	v_mfma_f32_16x16x32_bf16 v[34:37], v[160:163], v[148:151], v[34:37]
	global_load_dwordx4 v[148:151], v247, s[36:37] offset:1152
	v_mfma_f32_16x16x32_bf16 v[54:57], v[132:135], v[152:155], v[54:57]
	s_waitcnt vmcnt(8)
	ds_write_b128 v19, v[144:147] offset:12288
	v_mfma_f32_16x16x32_bf16 v[66:69], v[140:143], v[152:155], v[66:69]
	ds_read_b128 v[144:147], v20 offset:38912
	v_mfma_f32_16x16x32_bf16 v[70:73], v[156:159], v[152:155], v[70:73]
	ds_read_b128 v[184:187], v21 offset:55296
	v_mfma_f32_16x16x32_bf16 v[38:41], v[160:163], v[152:155], v[38:41]
	global_load_dwordx4 v[132:135], v18, s[6:7] offset:1152
	s_waitcnt vmcnt(8)
	ds_write_b128 v19, v[124:127] offset:16384
	s_waitcnt lgkmcnt(10)
	v_mfma_f32_16x16x32_bf16 v[42:45], v[172:175], v[164:167], v[42:45]
	s_waitcnt lgkmcnt(1)
	v_mfma_f32_16x16x32_bf16 v[26:29], v[184:187], v[164:167], v[26:29]
	v_mfma_f32_16x16x32_bf16 v[96:99], v[176:179], v[164:167], v[96:99]
	v_mfma_f32_16x16x32_bf16 v[104:107], v[180:183], v[164:167], v[104:107]
	global_load_dwordx4 v[124:127], v248, s[6:7] offset:1152
	v_mfma_f32_16x16x32_bf16 v[46:49], v[172:175], v[78:81], v[46:49]
	s_waitcnt vmcnt(8)
	ds_write_b128 v19, v[136:139] offset:20480
	v_mfma_f32_16x16x32_bf16 v[58:61], v[176:179], v[78:81], v[58:61]
	v_mfma_f32_16x16x32_bf16 v[30:33], v[184:187], v[78:81], v[30:33]
	v_mfma_f32_16x16x32_bf16 v[100:103], v[180:183], v[78:81], v[100:103]
	global_load_dwordx4 v[78:81], v249, s[6:7] offset:1152
	v_mfma_f32_16x16x32_bf16 v[50:53], v[172:175], v[116:119], v[50:53]
	s_waitcnt vmcnt(8)
	ds_write_b128 v19, v[108:111] offset:24576
	v_mfma_f32_16x16x32_bf16 v[62:65], v[176:179], v[116:119], v[62:65]
	v_mfma_f32_16x16x32_bf16 v[74:77], v[180:183], v[116:119], v[74:77]
	v_mfma_f32_16x16x32_bf16 v[34:37], v[184:187], v[116:119], v[34:37]
	global_load_dwordx4 v[108:111], v250, s[6:7] offset:1152
	v_mfma_f32_16x16x32_bf16 v[54:57], v[172:175], v[144:147], v[54:57]
	s_waitcnt vmcnt(8)
	ds_write_b128 v19, v[92:95] offset:28672
	v_mfma_f32_16x16x32_bf16 v[66:69], v[176:179], v[144:147], v[66:69]
	v_mfma_f32_16x16x32_bf16 v[70:73], v[180:183], v[144:147], v[70:73]
	v_mfma_f32_16x16x32_bf16 v[38:41], v[184:187], v[144:147], v[38:41]
	s_setprio 0
	s_waitcnt lgkmcnt(0)
	s_barrier
; template <int MODE>
; __device__ __forceinline__ void gemm_tile(const Params& P, int tm, int tn, unsigned char* smem) {
;     ...
; #pragma unroll
;         for (int i = 0; i < 4; ++i) { fa[i] = *(const bf16x8*)(sA + arow_off + i * 2048 + ch0); fb[i] = *(const bf16x8*)(sB + brow_off + i * 2048 + ch0); }
;         __builtin_amdgcn_sched_barrier(0);
;         __builtin_amdgcn_s_setprio(2);
;         if (wr_ok) *(uint4*)(nA + soff0) = ra0;
;         if (ld_ok) ra0 = *(const uint4*)(Ab + (aoff + 0u * LDA + koa));
;         ga[0] = *(const bf16x8*)(sA + arow_off + 0 * 2048 + ch1); gb[0] = *(const bf16x8*)(sB + brow_off + 0 * 2048 + ch1);
;         __builtin_amdgcn_sched_barrier(0);
; #pragma unroll
;         for (int j = 0; j < 4; ++j) acc[0][j] = __builtin_amdgcn_mfma_f32_16x16x32_bf16(fb[j], fa[0], acc[0][j], 0, 0, 0);
;         __builtin_amdgcn_sched_barrier(0);
;         if (wr_ok) *(uint4*)(nA + soff0 + 4096) = ra1;
;         if (ld_ok) ra1 = *(const uint4*)(Ab + (aoff + 32u * LDA + koa));
;         ga[1] = *(const bf16x8*)(sA + arow_off + 1 * 2048 + ch1); gb[1] = *(const bf16x8*)(sB + brow_off + 1 * 2048 + ch1);
;         __builtin_amdgcn_sched_barrier(0);
; #pragma unroll
;         for (int j = 0; j < 4; ++j) acc[1][j] = __builtin_amdgcn_mfma_f32_16x16x32_bf16(fb[j], fa[1], acc[1][j], 0, 0, 0);
;         __builtin_amdgcn_sched_barrier(0);
;         if (wr_ok) *(uint4*)(nA + soff0 + 8192) = ra2;
;         if (ld_ok) ra2 = *(const uint4*)(Ab + (aoff + 64u * LDA + koa));
;         ga[2] = *(const bf16x8*)(sA + arow_off + 2 * 2048 + ch1); gb[2] = *(const bf16x8*)(sB + brow_off + 2 * 2048 + ch1);
;         __builtin_amdgcn_sched_barrier(0);
; #pragma unroll
;         for (int j = 0; j < 4; ++j) acc[2][j] = __builtin_amdgcn_mfma_f32_16x16x32_bf16(fb[j], fa[2], acc[2][j], 0, 0, 0);
;         __builtin_amdgcn_sched_barrier(0);
;         if (wr_ok) *(uint4*)(nA + soff0 + 12288) = ra3;
;         if (ld_ok) ra3 = *(const uint4*)(Ab + (aoff + 96u * LDA + koa));
;         ga[3] = *(const bf16x8*)(sA + arow_off + 3 * 2048 + ch1); gb[3] = *(const bf16x8*)(sB + brow_off + 3 * 2048 + ch1);
;         __builtin_amdgcn_sched_barrier(0);
; #pragma unroll
;         for (int j = 0; j < 4; ++j) acc[3][j] = __builtin_amdgcn_mfma_f32_16x16x32_bf16(fb[j], fa[3], acc[3][j], 0, 0, 0);
;         __builtin_amdgcn_sched_barrier(0);
;         if (wr_ok) *(uint4*)(nB + soff0) = rb0;
	ds_read_b128 v[92:95], v22
	ds_read_b128 v[116:119], v22 offset:2048
	ds_read_b128 v[136:139], v23 offset:16384
	ds_read_b128 v[140:143], v23 offset:18432
	ds_read_b128 v[144:147], v22 offset:4096
	ds_read_b128 v[152:155], v22 offset:6144
	ds_read_b128 v[156:159], v23 offset:20480
	ds_read_b128 v[160:163], v23 offset:22528
	s_setprio 2
	global_load_dwordx4 v[164:167], v24, s[36:37] offset:1280
	s_waitcnt vmcnt(8)
	ds_write_b128 v19, v[168:171] offset:32768
	ds_read_b128 v[168:171], v20
	ds_read_b128 v[172:175], v21 offset:16384
	s_waitcnt lgkmcnt(8)
	v_mfma_f32_16x16x32_bf16 v[42:45], v[136:139], v[92:95], v[42:45]
	s_waitcnt lgkmcnt(3)
	v_mfma_f32_16x16x32_bf16 v[26:29], v[160:163], v[92:95], v[26:29]
	v_mfma_f32_16x16x32_bf16 v[96:99], v[140:143], v[92:95], v[96:99]
	v_mfma_f32_16x16x32_bf16 v[104:107], v[156:159], v[92:95], v[104:107]
	global_load_dwordx4 v[92:95], v245, s[36:37] offset:1280
	v_mfma_f32_16x16x32_bf16 v[46:49], v[136:139], v[116:119], v[46:49]
	s_waitcnt vmcnt(8)
	ds_write_b128 v19, v[112:115] offset:36864
	v_mfma_f32_16x16x32_bf16 v[58:61], v[140:143], v[116:119], v[58:61]
	ds_read_b128 v[112:115], v20 offset:2048
	v_mfma_f32_16x16x32_bf16 v[30:33], v[160:163], v[116:119], v[30:33]
	ds_read_b128 v[176:179], v21 offset:18432
	v_mfma_f32_16x16x32_bf16 v[100:103], v[156:159], v[116:119], v[100:103]
	global_load_dwordx4 v[116:119], v246, s[36:37] offset:1280
	v_mfma_f32_16x16x32_bf16 v[50:53], v[136:139], v[144:147], v[50:53]
	s_waitcnt vmcnt(8)
	ds_write_b128 v19, v[120:123] offset:40960
	v_mfma_f32_16x16x32_bf16 v[62:65], v[140:143], v[144:147], v[62:65]
	ds_read_b128 v[120:123], v20 offset:4096
	v_mfma_f32_16x16x32_bf16 v[74:77], v[156:159], v[144:147], v[74:77]
	ds_read_b128 v[180:183], v21 offset:20480
	v_mfma_f32_16x16x32_bf16 v[34:37], v[160:163], v[144:147], v[34:37]
	global_load_dwordx4 v[144:147], v247, s[36:37] offset:1280
	v_mfma_f32_16x16x32_bf16 v[54:57], v[136:139], v[152:155], v[54:57]
	s_waitcnt vmcnt(8)
	ds_write_b128 v19, v[148:151] offset:45056
	v_mfma_f32_16x16x32_bf16 v[66:69], v[140:143], v[152:155], v[66:69]
	ds_read_b128 v[148:151], v20 offset:6144
	v_mfma_f32_16x16x32_bf16 v[70:73], v[156:159], v[152:155], v[70:73]
	ds_read_b128 v[184:187], v21 offset:22528
	v_mfma_f32_16x16x32_bf16 v[38:41], v[160:163], v[152:155], v[38:41]
	global_load_dwordx4 v[136:139], v18, s[6:7] offset:1280
	s_waitcnt vmcnt(8)
	ds_write_b128 v19, v[132:135] offset:49152
	s_waitcnt lgkmcnt(10)
	v_mfma_f32_16x16x32_bf16 v[42:45], v[172:175], v[168:171], v[42:45]
	s_waitcnt lgkmcnt(1)
	v_mfma_f32_16x16x32_bf16 v[26:29], v[184:187], v[168:171], v[26:29]
	v_mfma_f32_16x16x32_bf16 v[96:99], v[176:179], v[168:171], v[96:99]
	v_mfma_f32_16x16x32_bf16 v[104:107], v[180:183], v[168:171], v[104:107]
	global_load_dwordx4 v[132:135], v248, s[6:7] offset:1280
	v_mfma_f32_16x16x32_bf16 v[46:49], v[172:175], v[112:115], v[46:49]
	s_waitcnt vmcnt(8)
	ds_write_b128 v19, v[124:127] offset:53248
	v_mfma_f32_16x16x32_bf16 v[58:61], v[176:179], v[112:115], v[58:61]
	v_mfma_f32_16x16x32_bf16 v[30:33], v[184:187], v[112:115], v[30:33]
	v_mfma_f32_16x16x32_bf16 v[100:103], v[180:183], v[112:115], v[100:103]
	global_load_dwordx4 v[112:115], v249, s[6:7] offset:1280
	v_mfma_f32_16x16x32_bf16 v[50:53], v[172:175], v[120:123], v[50:53]
	s_waitcnt vmcnt(8)
	ds_write_b128 v19, v[78:81] offset:57344
	v_mfma_f32_16x16x32_bf16 v[62:65], v[176:179], v[120:123], v[62:65]
	v_mfma_f32_16x16x32_bf16 v[74:77], v[180:183], v[120:123], v[74:77]
	v_mfma_f32_16x16x32_bf16 v[34:37], v[184:187], v[120:123], v[34:37]
	global_load_dwordx4 v[78:81], v250, s[6:7] offset:1280
	v_mfma_f32_16x16x32_bf16 v[54:57], v[172:175], v[148:151], v[54:57]
	s_waitcnt vmcnt(8)
	ds_write_b128 v19, v[108:111] offset:61440
	v_mfma_f32_16x16x32_bf16 v[66:69], v[176:179], v[148:151], v[66:69]
	v_mfma_f32_16x16x32_bf16 v[70:73], v[180:183], v[148:151], v[70:73]
	v_mfma_f32_16x16x32_bf16 v[38:41], v[184:187], v[148:151], v[38:41]
	s_setprio 0
	s_waitcnt lgkmcnt(0)
	s_barrier
	ds_read_b128 v[108:111], v22 offset:32768
	ds_read_b128 v[120:123], v22 offset:34816
	ds_read_b128 v[124:127], v23 offset:49152
	ds_read_b128 v[140:143], v23 offset:51200
	ds_read_b128 v[148:151], v22 offset:36864
	ds_read_b128 v[152:155], v22 offset:38912
	ds_read_b128 v[156:159], v23 offset:53248
	ds_read_b128 v[160:163], v23 offset:55296
	s_setprio 2
	global_load_dwordx4 v[168:171], v24, s[36:37] offset:1408
	s_waitcnt vmcnt(8)
	ds_write_b128 v19, v[164:167]
	ds_read_b128 v[164:167], v20 offset:32768
	ds_read_b128 v[172:175], v21 offset:49152
	s_waitcnt lgkmcnt(8)
	v_mfma_f32_16x16x32_bf16 v[42:45], v[124:127], v[108:111], v[42:45]
	s_waitcnt lgkmcnt(3)
	v_mfma_f32_16x16x32_bf16 v[26:29], v[160:163], v[108:111], v[26:29]
	v_mfma_f32_16x16x32_bf16 v[96:99], v[140:143], v[108:111], v[96:99]
	v_mfma_f32_16x16x32_bf16 v[104:107], v[156:159], v[108:111], v[104:107]
	global_load_dwordx4 v[108:111], v245, s[36:37] offset:1408
	v_mfma_f32_16x16x32_bf16 v[46:49], v[124:127], v[120:123], v[46:49]
	s_waitcnt vmcnt(8)
	ds_write_b128 v19, v[92:95] offset:4096
	v_mfma_f32_16x16x32_bf16 v[58:61], v[140:143], v[120:123], v[58:61]
	ds_read_b128 v[92:95], v20 offset:34816
	v_mfma_f32_16x16x32_bf16 v[30:33], v[160:163], v[120:123], v[30:33]
	ds_read_b128 v[176:179], v21 offset:51200
	v_mfma_f32_16x16x32_bf16 v[100:103], v[156:159], v[120:123], v[100:103]
	global_load_dwordx4 v[120:123], v246, s[36:37] offset:1408
	v_mfma_f32_16x16x32_bf16 v[50:53], v[124:127], v[148:151], v[50:53]
	s_waitcnt vmcnt(8)
; template <int MODE>
; __device__ __forceinline__ void gemm_tile(const Params& P, int tm, int tn, unsigned char* smem) {
;     ...
; #pragma unroll
;         for (int i = 0; i < 4; ++i) { fa[i] = *(const bf16x8*)(sA + arow_off + i * 2048 + ch0); fb[i] = *(const bf16x8*)(sB + brow_off + i * 2048 + ch0); }
;         __builtin_amdgcn_sched_barrier(0);
;         __builtin_amdgcn_s_setprio(2);
;         if (wr_ok) *(uint4*)(nA + soff0) = ra0;
;         if (ld_ok) ra0 = *(const uint4*)(Ab + (aoff + 0u * LDA + koa));
;         ga[0] = *(const bf16x8*)(sA + arow_off + 0 * 2048 + ch1); gb[0] = *(const bf16x8*)(sB + brow_off + 0 * 2048 + ch1);
;         __builtin_amdgcn_sched_barrier(0);
; #pragma unroll
;         for (int j = 0; j < 4; ++j) acc[0][j] = __builtin_amdgcn_mfma_f32_16x16x32_bf16(fb[j], fa[0], acc[0][j], 0, 0, 0);
;         __builtin_amdgcn_sched_barrier(0);
;         if (wr_ok) *(uint4*)(nA + soff0 + 4096) = ra1;
;         if (ld_ok) ra1 = *(const uint4*)(Ab + (aoff + 32u * LDA + koa));
;         ga[1] = *(const bf16x8*)(sA + arow_off + 1 * 2048 + ch1); gb[1] = *(const bf16x8*)(sB + brow_off + 1 * 2048 + ch1);
;         __builtin_amdgcn_sched_barrier(0);
; #pragma unroll
;         for (int j = 0; j < 4; ++j) acc[1][j] = __builtin_amdgcn_mfma_f32_16x16x32_bf16(fb[j], fa[1], acc[1][j], 0, 0, 0);
;         __builtin_amdgcn_sched_barrier(0);
;         if (wr_ok) *(uint4*)(nA + soff0 + 8192) = ra2;
;         if (ld_ok) ra2 = *(const uint4*)(Ab + (aoff + 64u * LDA + koa));
;         ga[2] = *(const bf16x8*)(sA + arow_off + 2 * 2048 + ch1); gb[2] = *(const bf16x8*)(sB + brow_off + 2 * 2048 + ch1);
;         __builtin_amdgcn_sched_barrier(0);
; #pragma unroll
;         for (int j = 0; j < 4; ++j) acc[2][j] = __builtin_amdgcn_mfma_f32_16x16x32_bf16(fb[j], fa[2], acc[2][j], 0, 0, 0);
;         __builtin_amdgcn_sched_barrier(0);
;         if (wr_ok) *(uint4*)(nA + soff0 + 12288) = ra3;
;         if (ld_ok) ra3 = *(const uint4*)(Ab + (aoff + 96u * LDA + koa));
;         ga[3] = *(const bf16x8*)(sA + arow_off + 3 * 2048 + ch1); gb[3] = *(const bf16x8*)(sB + brow_off + 3 * 2048 + ch1);
;         __builtin_amdgcn_sched_barrier(0);
; #pragma unroll
;         for (int j = 0; j < 4; ++j) acc[3][j] = __builtin_amdgcn_mfma_f32_16x16x32_bf16(fb[j], fa[3], acc[3][j], 0, 0, 0);
;         __builtin_amdgcn_sched_barrier(0);
;         if (wr_ok) *(uint4*)(nB + soff0) = rb0;
	ds_write_b128 v19, v[116:119] offset:8192
	v_mfma_f32_16x16x32_bf16 v[62:65], v[140:143], v[148:151], v[62:65]
	ds_read_b128 v[116:119], v20 offset:36864
	v_mfma_f32_16x16x32_bf16 v[74:77], v[156:159], v[148:151], v[74:77]
	ds_read_b128 v[180:183], v21 offset:53248
	v_mfma_f32_16x16x32_bf16 v[34:37], v[160:163], v[148:151], v[34:37]
	global_load_dwordx4 v[148:151], v247, s[36:37] offset:1408
	v_mfma_f32_16x16x32_bf16 v[54:57], v[124:127], v[152:155], v[54:57]
	s_waitcnt vmcnt(8)
	ds_write_b128 v19, v[144:147] offset:12288
	v_mfma_f32_16x16x32_bf16 v[66:69], v[140:143], v[152:155], v[66:69]
	ds_read_b128 v[144:147], v20 offset:38912
	v_mfma_f32_16x16x32_bf16 v[70:73], v[156:159], v[152:155], v[70:73]
	ds_read_b128 v[184:187], v21 offset:55296
	v_mfma_f32_16x16x32_bf16 v[38:41], v[160:163], v[152:155], v[38:41]
	global_load_dwordx4 v[124:127], v18, s[6:7] offset:1408
	s_waitcnt vmcnt(8)
	ds_write_b128 v19, v[136:139] offset:16384
	s_waitcnt lgkmcnt(10)
	v_mfma_f32_16x16x32_bf16 v[42:45], v[172:175], v[164:167], v[42:45]
	s_waitcnt lgkmcnt(1)
	v_mfma_f32_16x16x32_bf16 v[26:29], v[184:187], v[164:167], v[26:29]
	v_mfma_f32_16x16x32_bf16 v[96:99], v[176:179], v[164:167], v[96:99]
	v_mfma_f32_16x16x32_bf16 v[104:107], v[180:183], v[164:167], v[104:107]
	global_load_dwordx4 v[136:139], v248, s[6:7] offset:1408
	v_mfma_f32_16x16x32_bf16 v[46:49], v[172:175], v[92:95], v[46:49]
	s_waitcnt vmcnt(8)
	ds_write_b128 v19, v[132:135] offset:20480
	v_mfma_f32_16x16x32_bf16 v[58:61], v[176:179], v[92:95], v[58:61]
	v_mfma_f32_16x16x32_bf16 v[30:33], v[184:187], v[92:95], v[30:33]
	v_mfma_f32_16x16x32_bf16 v[100:103], v[180:183], v[92:95], v[100:103]
	global_load_dwordx4 v[92:95], v249, s[6:7] offset:1408
	v_mfma_f32_16x16x32_bf16 v[50:53], v[172:175], v[116:119], v[50:53]
	s_waitcnt vmcnt(8)
	ds_write_b128 v19, v[112:115] offset:24576
	v_mfma_f32_16x16x32_bf16 v[62:65], v[176:179], v[116:119], v[62:65]
	v_mfma_f32_16x16x32_bf16 v[74:77], v[180:183], v[116:119], v[74:77]
	v_mfma_f32_16x16x32_bf16 v[34:37], v[184:187], v[116:119], v[34:37]
	global_load_dwordx4 v[112:115], v250, s[6:7] offset:1408
	v_mfma_f32_16x16x32_bf16 v[54:57], v[172:175], v[144:147], v[54:57]
	s_waitcnt vmcnt(8)
	ds_write_b128 v19, v[78:81] offset:28672
	v_mfma_f32_16x16x32_bf16 v[66:69], v[176:179], v[144:147], v[66:69]
	v_mfma_f32_16x16x32_bf16 v[70:73], v[180:183], v[144:147], v[70:73]
	v_mfma_f32_16x16x32_bf16 v[38:41], v[184:187], v[144:147], v[38:41]
	s_setprio 0
	s_waitcnt lgkmcnt(0)
	s_barrier
	ds_read_b128 v[78:81], v22
	ds_read_b128 v[116:119], v22 offset:2048
	ds_read_b128 v[132:135], v23 offset:16384
	ds_read_b128 v[140:143], v23 offset:18432
	ds_read_b128 v[144:147], v22 offset:4096
	ds_read_b128 v[152:155], v22 offset:6144
	ds_read_b128 v[156:159], v23 offset:20480
	ds_read_b128 v[160:163], v23 offset:22528
	s_setprio 2
	global_load_dwordx4 v[164:167], v24, s[36:37] offset:1536
	s_waitcnt vmcnt(8)
	ds_write_b128 v19, v[168:171] offset:32768
	ds_read_b128 v[168:171], v20
	ds_read_b128 v[172:175], v21 offset:16384
	s_waitcnt lgkmcnt(8)
	v_mfma_f32_16x16x32_bf16 v[42:45], v[132:135], v[78:81], v[42:45]
	s_waitcnt lgkmcnt(3)
	v_mfma_f32_16x16x32_bf16 v[26:29], v[160:163], v[78:81], v[26:29]
	v_mfma_f32_16x16x32_bf16 v[96:99], v[140:143], v[78:81], v[96:99]
	v_mfma_f32_16x16x32_bf16 v[104:107], v[156:159], v[78:81], v[104:107]
	global_load_dwordx4 v[78:81], v245, s[36:37] offset:1536
	v_mfma_f32_16x16x32_bf16 v[46:49], v[132:135], v[116:119], v[46:49]
	s_waitcnt vmcnt(8)
	ds_write_b128 v19, v[108:111] offset:36864
	v_mfma_f32_16x16x32_bf16 v[58:61], v[140:143], v[116:119], v[58:61]
	ds_read_b128 v[108:111], v20 offset:2048
	v_mfma_f32_16x16x32_bf16 v[30:33], v[160:163], v[116:119], v[30:33]
	ds_read_b128 v[176:179], v21 offset:18432
	v_mfma_f32_16x16x32_bf16 v[100:103], v[156:159], v[116:119], v[100:103]
	global_load_dwordx4 v[116:119], v246, s[36:37] offset:1536
	v_mfma_f32_16x16x32_bf16 v[50:53], v[132:135], v[144:147], v[50:53]
	s_waitcnt vmcnt(8)
	ds_write_b128 v19, v[120:123] offset:40960
	v_mfma_f32_16x16x32_bf16 v[62:65], v[140:143], v[144:147], v[62:65]
	ds_read_b128 v[120:123], v20 offset:4096
	v_mfma_f32_16x16x32_bf16 v[74:77], v[156:159], v[144:147], v[74:77]
	ds_read_b128 v[180:183], v21 offset:20480
	v_mfma_f32_16x16x32_bf16 v[34:37], v[160:163], v[144:147], v[34:37]
	global_load_dwordx4 v[144:147], v247, s[36:37] offset:1536
	v_mfma_f32_16x16x32_bf16 v[54:57], v[132:135], v[152:155], v[54:57]
	s_waitcnt vmcnt(8)
	ds_write_b128 v19, v[148:151] offset:45056
	v_mfma_f32_16x16x32_bf16 v[66:69], v[140:143], v[152:155], v[66:69]
	ds_read_b128 v[148:151], v20 offset:6144
	v_mfma_f32_16x16x32_bf16 v[70:73], v[156:159], v[152:155], v[70:73]
	ds_read_b128 v[184:187], v21 offset:22528
	v_mfma_f32_16x16x32_bf16 v[38:41], v[160:163], v[152:155], v[38:41]
	global_load_dwordx4 v[132:135], v18, s[6:7] offset:1536
	s_waitcnt vmcnt(8)
	ds_write_b128 v19, v[124:127] offset:49152
	s_waitcnt lgkmcnt(10)
	v_mfma_f32_16x16x32_bf16 v[42:45], v[172:175], v[168:171], v[42:45]
	s_waitcnt lgkmcnt(1)
	v_mfma_f32_16x16x32_bf16 v[26:29], v[184:187], v[168:171], v[26:29]
	v_mfma_f32_16x16x32_bf16 v[96:99], v[176:179], v[168:171], v[96:99]
	v_mfma_f32_16x16x32_bf16 v[104:107], v[180:183], v[168:171], v[104:107]
	global_load_dwordx4 v[124:127], v248, s[6:7] offset:1536
	v_mfma_f32_16x16x32_bf16 v[46:49], v[172:175], v[108:111], v[46:49]
	s_waitcnt vmcnt(8)
	ds_write_b128 v19, v[136:139] offset:53248
	v_mfma_f32_16x16x32_bf16 v[58:61], v[176:179], v[108:111], v[58:61]
	v_mfma_f32_16x16x32_bf16 v[30:33], v[184:187], v[108:111], v[30:33]
	v_mfma_f32_16x16x32_bf16 v[100:103], v[180:183], v[108:111], v[100:103]
	global_load_dwordx4 v[108:111], v249, s[6:7] offset:1536
	v_mfma_f32_16x16x32_bf16 v[50:53], v[172:175], v[120:123], v[50:53]
	s_waitcnt vmcnt(8)
	ds_write_b128 v19, v[92:95] offset:57344
	v_mfma_f32_16x16x32_bf16 v[62:65], v[176:179], v[120:123], v[62:65]
	v_mfma_f32_16x16x32_bf16 v[74:77], v[180:183], v[120:123], v[74:77]
	v_mfma_f32_16x16x32_bf16 v[34:37], v[184:187], v[120:123], v[34:37]
	global_load_dwordx4 v[92:95], v250, s[6:7] offset:1536
	v_mfma_f32_16x16x32_bf16 v[54:57], v[172:175], v[148:151], v[54:57]
	s_waitcnt vmcnt(8)
	ds_write_b128 v19, v[112:115] offset:61440
	v_mfma_f32_16x16x32_bf16 v[66:69], v[176:179], v[148:151], v[66:69]
	v_mfma_f32_16x16x32_bf16 v[70:73], v[180:183], v[148:151], v[70:73]
	v_mfma_f32_16x16x32_bf16 v[38:41], v[184:187], v[148:151], v[38:41]
	s_setprio 0
	s_waitcnt lgkmcnt(0)
	s_barrier
; template <int MODE>
; __device__ __forceinline__ void gemm_tile(const Params& P, int tm, int tn, unsigned char* smem) {
;     ...
; #pragma unroll
;         for (int i = 0; i < 4; ++i) { fa[i] = *(const bf16x8*)(sA + arow_off + i * 2048 + ch0); fb[i] = *(const bf16x8*)(sB + brow_off + i * 2048 + ch0); }
;         __builtin_amdgcn_sched_barrier(0);
;         __builtin_amdgcn_s_setprio(2);
;         if (wr_ok) *(uint4*)(nA + soff0) = ra0;
;         if (ld_ok) ra0 = *(const uint4*)(Ab + (aoff + 0u * LDA + koa));
;         ga[0] = *(const bf16x8*)(sA + arow_off + 0 * 2048 + ch1); gb[0] = *(const bf16x8*)(sB + brow_off + 0 * 2048 + ch1);
;         __builtin_amdgcn_sched_barrier(0);
; #pragma unroll
;         for (int j = 0; j < 4; ++j) acc[0][j] = __builtin_amdgcn_mfma_f32_16x16x32_bf16(fb[j], fa[0], acc[0][j], 0, 0, 0);
;         __builtin_amdgcn_sched_barrier(0);
;         if (wr_ok) *(uint4*)(nA + soff0 + 4096) = ra1;
;         if (ld_ok) ra1 = *(const uint4*)(Ab + (aoff + 32u * LDA + koa));
;         ga[1] = *(const bf16x8*)(sA + arow_off + 1 * 2048 + ch1); gb[1] = *(const bf16x8*)(sB + brow_off + 1 * 2048 + ch1);
;         __builtin_amdgcn_sched_barrier(0);
; #pragma unroll
;         for (int j = 0; j < 4; ++j) acc[1][j] = __builtin_amdgcn_mfma_f32_16x16x32_bf16(fb[j], fa[1], acc[1][j], 0, 0, 0);
;         __builtin_amdgcn_sched_barrier(0);
;         if (wr_ok) *(uint4*)(nA + soff0 + 8192) = ra2;
;         if (ld_ok) ra2 = *(const uint4*)(Ab + (aoff + 64u * LDA + koa));
;         ga[2] = *(const bf16x8*)(sA + arow_off + 2 * 2048 + ch1); gb[2] = *(const bf16x8*)(sB + brow_off + 2 * 2048 + ch1);
;         __builtin_amdgcn_sched_barrier(0);
; #pragma unroll
;         for (int j = 0; j < 4; ++j) acc[2][j] = __builtin_amdgcn_mfma_f32_16x16x32_bf16(fb[j], fa[2], acc[2][j], 0, 0, 0);
;         __builtin_amdgcn_sched_barrier(0);
;         if (wr_ok) *(uint4*)(nA + soff0 + 12288) = ra3;
;         if (ld_ok) ra3 = *(const uint4*)(Ab + (aoff + 96u * LDA + koa));
;         ga[3] = *(const bf16x8*)(sA + arow_off + 3 * 2048 + ch1); gb[3] = *(const bf16x8*)(sB + brow_off + 3 * 2048 + ch1);
;         __builtin_amdgcn_sched_barrier(0);
; #pragma unroll
;         for (int j = 0; j < 4; ++j) acc[3][j] = __builtin_amdgcn_mfma_f32_16x16x32_bf16(fb[j], fa[3], acc[3][j], 0, 0, 0);
;         __builtin_amdgcn_sched_barrier(0);
;         if (wr_ok) *(uint4*)(nB + soff0) = rb0;
	ds_read_b128 v[112:115], v22 offset:32768
	ds_read_b128 v[120:123], v22 offset:34816
	ds_read_b128 v[136:139], v23 offset:49152
	ds_read_b128 v[140:143], v23 offset:51200
	ds_read_b128 v[148:151], v22 offset:36864
	ds_read_b128 v[152:155], v22 offset:38912
	ds_read_b128 v[156:159], v23 offset:53248
	ds_read_b128 v[160:163], v23 offset:55296
	s_setprio 2
	global_load_dwordx4 v[168:171], v24, s[36:37] offset:1664
	s_waitcnt vmcnt(8)
	ds_write_b128 v19, v[164:167]
	ds_read_b128 v[164:167], v20 offset:32768
	ds_read_b128 v[172:175], v21 offset:49152
	s_waitcnt lgkmcnt(8)
	v_mfma_f32_16x16x32_bf16 v[42:45], v[136:139], v[112:115], v[42:45]
	s_waitcnt lgkmcnt(3)
	v_mfma_f32_16x16x32_bf16 v[26:29], v[160:163], v[112:115], v[26:29]
	v_mfma_f32_16x16x32_bf16 v[96:99], v[140:143], v[112:115], v[96:99]
	v_mfma_f32_16x16x32_bf16 v[104:107], v[156:159], v[112:115], v[104:107]
	global_load_dwordx4 v[112:115], v245, s[36:37] offset:1664
	v_mfma_f32_16x16x32_bf16 v[46:49], v[136:139], v[120:123], v[46:49]
	s_waitcnt vmcnt(8)
	ds_write_b128 v19, v[78:81] offset:4096
	v_mfma_f32_16x16x32_bf16 v[58:61], v[140:143], v[120:123], v[58:61]
	ds_read_b128 v[78:81], v20 offset:34816
	v_mfma_f32_16x16x32_bf16 v[30:33], v[160:163], v[120:123], v[30:33]
	ds_read_b128 v[176:179], v21 offset:51200
	v_mfma_f32_16x16x32_bf16 v[100:103], v[156:159], v[120:123], v[100:103]
	global_load_dwordx4 v[120:123], v246, s[36:37] offset:1664
	v_mfma_f32_16x16x32_bf16 v[50:53], v[136:139], v[148:151], v[50:53]
	s_waitcnt vmcnt(8)
	ds_write_b128 v19, v[116:119] offset:8192
	v_mfma_f32_16x16x32_bf16 v[62:65], v[140:143], v[148:151], v[62:65]
	ds_read_b128 v[116:119], v20 offset:36864
	v_mfma_f32_16x16x32_bf16 v[74:77], v[156:159], v[148:151], v[74:77]
	ds_read_b128 v[180:183], v21 offset:53248
	v_mfma_f32_16x16x32_bf16 v[34:37], v[160:163], v[148:151], v[34:37]
	global_load_dwordx4 v[148:151], v247, s[36:37] offset:1664
	v_mfma_f32_16x16x32_bf16 v[54:57], v[136:139], v[152:155], v[54:57]
	s_waitcnt vmcnt(8)
	ds_write_b128 v19, v[144:147] offset:12288
	v_mfma_f32_16x16x32_bf16 v[66:69], v[140:143], v[152:155], v[66:69]
	ds_read_b128 v[144:147], v20 offset:38912
	v_mfma_f32_16x16x32_bf16 v[70:73], v[156:159], v[152:155], v[70:73]
	ds_read_b128 v[184:187], v21 offset:55296
	v_mfma_f32_16x16x32_bf16 v[38:41], v[160:163], v[152:155], v[38:41]
	global_load_dwordx4 v[136:139], v18, s[6:7] offset:1664
	s_waitcnt vmcnt(8)
	ds_write_b128 v19, v[132:135] offset:16384
	s_waitcnt lgkmcnt(10)
	v_mfma_f32_16x16x32_bf16 v[42:45], v[172:175], v[164:167], v[42:45]
	s_waitcnt lgkmcnt(1)
	v_mfma_f32_16x16x32_bf16 v[26:29], v[184:187], v[164:167], v[26:29]
	v_mfma_f32_16x16x32_bf16 v[96:99], v[176:179], v[164:167], v[96:99]
	v_mfma_f32_16x16x32_bf16 v[104:107], v[180:183], v[164:167], v[104:107]
	global_load_dwordx4 v[132:135], v248, s[6:7] offset:1664
	v_mfma_f32_16x16x32_bf16 v[46:49], v[172:175], v[78:81], v[46:49]
	s_waitcnt vmcnt(8)
	ds_write_b128 v19, v[124:127] offset:20480
	v_mfma_f32_16x16x32_bf16 v[58:61], v[176:179], v[78:81], v[58:61]
	v_mfma_f32_16x16x32_bf16 v[30:33], v[184:187], v[78:81], v[30:33]
	v_mfma_f32_16x16x32_bf16 v[100:103], v[180:183], v[78:81], v[100:103]
	global_load_dwordx4 v[78:81], v249, s[6:7] offset:1664
	v_mfma_f32_16x16x32_bf16 v[50:53], v[172:175], v[116:119], v[50:53]
	s_waitcnt vmcnt(8)
	ds_write_b128 v19, v[108:111] offset:24576
	v_mfma_f32_16x16x32_bf16 v[62:65], v[176:179], v[116:119], v[62:65]
	v_mfma_f32_16x16x32_bf16 v[74:77], v[180:183], v[116:119], v[74:77]
	v_mfma_f32_16x16x32_bf16 v[34:37], v[184:187], v[116:119], v[34:37]
	global_load_dwordx4 v[108:111], v250, s[6:7] offset:1664
	v_mfma_f32_16x16x32_bf16 v[54:57], v[172:175], v[144:147], v[54:57]
	s_waitcnt vmcnt(8)
	ds_write_b128 v19, v[92:95] offset:28672
	v_mfma_f32_16x16x32_bf16 v[66:69], v[176:179], v[144:147], v[66:69]
	v_mfma_f32_16x16x32_bf16 v[70:73], v[180:183], v[144:147], v[70:73]
	v_mfma_f32_16x16x32_bf16 v[38:41], v[184:187], v[144:147], v[38:41]
	s_setprio 0
	s_waitcnt lgkmcnt(0)
	s_barrier
	ds_read_b128 v[92:95], v22
	ds_read_b128 v[116:119], v22 offset:2048
	ds_read_b128 v[124:127], v23 offset:16384
	ds_read_b128 v[140:143], v23 offset:18432
	ds_read_b128 v[144:147], v22 offset:4096
	ds_read_b128 v[152:155], v22 offset:6144
	ds_read_b128 v[156:159], v23 offset:20480
	ds_read_b128 v[160:163], v23 offset:22528
	s_setprio 2
	global_load_dwordx4 v[164:167], v24, s[36:37] offset:1792
	s_waitcnt vmcnt(8)
	ds_write_b128 v19, v[168:171] offset:32768
	ds_read_b128 v[168:171], v20
	ds_read_b128 v[172:175], v21 offset:16384
	s_waitcnt lgkmcnt(8)
	v_mfma_f32_16x16x32_bf16 v[42:45], v[124:127], v[92:95], v[42:45]
	s_waitcnt lgkmcnt(3)
	v_mfma_f32_16x16x32_bf16 v[26:29], v[160:163], v[92:95], v[26:29]
	v_mfma_f32_16x16x32_bf16 v[96:99], v[140:143], v[92:95], v[96:99]
	v_mfma_f32_16x16x32_bf16 v[104:107], v[156:159], v[92:95], v[104:107]
	global_load_dwordx4 v[92:95], v245, s[36:37] offset:1792
	v_mfma_f32_16x16x32_bf16 v[46:49], v[124:127], v[116:119], v[46:49]
	s_waitcnt vmcnt(8)
	ds_write_b128 v19, v[112:115] offset:36864
	v_mfma_f32_16x16x32_bf16 v[58:61], v[140:143], v[116:119], v[58:61]
	ds_read_b128 v[112:115], v20 offset:2048
	v_mfma_f32_16x16x32_bf16 v[30:33], v[160:163], v[116:119], v[30:33]
	ds_read_b128 v[176:179], v21 offset:18432
	v_mfma_f32_16x16x32_bf16 v[100:103], v[156:159], v[116:119], v[100:103]
	global_load_dwordx4 v[116:119], v246, s[36:37] offset:1792
	v_mfma_f32_16x16x32_bf16 v[50:53], v[124:127], v[144:147], v[50:53]
	s_waitcnt vmcnt(8)
; template <int MODE>
; __device__ __forceinline__ void gemm_tile(const Params& P, int tm, int tn, unsigned char* smem) {
;     ...
; #pragma unroll
;         for (int i = 0; i < 4; ++i) { fa[i] = *(const bf16x8*)(sA + arow_off + i * 2048 + ch0); fb[i] = *(const bf16x8*)(sB + brow_off + i * 2048 + ch0); }
;         __builtin_amdgcn_sched_barrier(0);
;         __builtin_amdgcn_s_setprio(2);
;         if (wr_ok) *(uint4*)(nA + soff0) = ra0;
;         if (ld_ok) ra0 = *(const uint4*)(Ab + (aoff + 0u * LDA + koa));
;         ga[0] = *(const bf16x8*)(sA + arow_off + 0 * 2048 + ch1); gb[0] = *(const bf16x8*)(sB + brow_off + 0 * 2048 + ch1);
;         __builtin_amdgcn_sched_barrier(0);
; #pragma unroll
;         for (int j = 0; j < 4; ++j) acc[0][j] = __builtin_amdgcn_mfma_f32_16x16x32_bf16(fb[j], fa[0], acc[0][j], 0, 0, 0);
;         __builtin_amdgcn_sched_barrier(0);
;         if (wr_ok) *(uint4*)(nA + soff0 + 4096) = ra1;
;         if (ld_ok) ra1 = *(const uint4*)(Ab + (aoff + 32u * LDA + koa));
;         ga[1] = *(const bf16x8*)(sA + arow_off + 1 * 2048 + ch1); gb[1] = *(const bf16x8*)(sB + brow_off + 1 * 2048 + ch1);
;         __builtin_amdgcn_sched_barrier(0);
; #pragma unroll
;         for (int j = 0; j < 4; ++j) acc[1][j] = __builtin_amdgcn_mfma_f32_16x16x32_bf16(fb[j], fa[1], acc[1][j], 0, 0, 0);
;         __builtin_amdgcn_sched_barrier(0);
;         if (wr_ok) *(uint4*)(nA + soff0 + 8192) = ra2;
;         if (ld_ok) ra2 = *(const uint4*)(Ab + (aoff + 64u * LDA + koa));
;         ga[2] = *(const bf16x8*)(sA + arow_off + 2 * 2048 + ch1); gb[2] = *(const bf16x8*)(sB + brow_off + 2 * 2048 + ch1);
;         __builtin_amdgcn_sched_barrier(0);
; #pragma unroll
;         for (int j = 0; j < 4; ++j) acc[2][j] = __builtin_amdgcn_mfma_f32_16x16x32_bf16(fb[j], fa[2], acc[2][j], 0, 0, 0);
;         __builtin_amdgcn_sched_barrier(0);
;         if (wr_ok) *(uint4*)(nA + soff0 + 12288) = ra3;
;         if (ld_ok) ra3 = *(const uint4*)(Ab + (aoff + 96u * LDA + koa));
;         ga[3] = *(const bf16x8*)(sA + arow_off + 3 * 2048 + ch1); gb[3] = *(const bf16x8*)(sB + brow_off + 3 * 2048 + ch1);
;         __builtin_amdgcn_sched_barrier(0);
; #pragma unroll
;         for (int j = 0; j < 4; ++j) acc[3][j] = __builtin_amdgcn_mfma_f32_16x16x32_bf16(fb[j], fa[3], acc[3][j], 0, 0, 0);
;         __builtin_amdgcn_sched_barrier(0);
;         if (wr_ok) *(uint4*)(nB + soff0) = rb0;
	ds_write_b128 v19, v[120:123] offset:40960
	v_mfma_f32_16x16x32_bf16 v[62:65], v[140:143], v[144:147], v[62:65]
	ds_read_b128 v[120:123], v20 offset:4096
	v_mfma_f32_16x16x32_bf16 v[74:77], v[156:159], v[144:147], v[74:77]
	ds_read_b128 v[180:183], v21 offset:20480
	v_mfma_f32_16x16x32_bf16 v[34:37], v[160:163], v[144:147], v[34:37]
	global_load_dwordx4 v[144:147], v247, s[36:37] offset:1792
	v_mfma_f32_16x16x32_bf16 v[54:57], v[124:127], v[152:155], v[54:57]
	s_waitcnt vmcnt(8)
	ds_write_b128 v19, v[148:151] offset:45056
	v_mfma_f32_16x16x32_bf16 v[66:69], v[140:143], v[152:155], v[66:69]
	ds_read_b128 v[148:151], v20 offset:6144
	v_mfma_f32_16x16x32_bf16 v[70:73], v[156:159], v[152:155], v[70:73]
	ds_read_b128 v[184:187], v21 offset:22528
	v_mfma_f32_16x16x32_bf16 v[38:41], v[160:163], v[152:155], v[38:41]
	global_load_dwordx4 v[124:127], v18, s[6:7] offset:1792
	s_waitcnt vmcnt(8)
	ds_write_b128 v19, v[136:139] offset:49152
	s_waitcnt lgkmcnt(10)
	v_mfma_f32_16x16x32_bf16 v[42:45], v[172:175], v[168:171], v[42:45]
	s_waitcnt lgkmcnt(1)
	v_mfma_f32_16x16x32_bf16 v[26:29], v[184:187], v[168:171], v[26:29]
	v_mfma_f32_16x16x32_bf16 v[96:99], v[176:179], v[168:171], v[96:99]
	v_mfma_f32_16x16x32_bf16 v[104:107], v[180:183], v[168:171], v[104:107]
	global_load_dwordx4 v[136:139], v248, s[6:7] offset:1792
	v_mfma_f32_16x16x32_bf16 v[46:49], v[172:175], v[112:115], v[46:49]
	s_waitcnt vmcnt(8)
	ds_write_b128 v19, v[132:135] offset:53248
	v_mfma_f32_16x16x32_bf16 v[58:61], v[176:179], v[112:115], v[58:61]
	v_mfma_f32_16x16x32_bf16 v[30:33], v[184:187], v[112:115], v[30:33]
	v_mfma_f32_16x16x32_bf16 v[100:103], v[180:183], v[112:115], v[100:103]
	global_load_dwordx4 v[112:115], v249, s[6:7] offset:1792
	v_mfma_f32_16x16x32_bf16 v[50:53], v[172:175], v[120:123], v[50:53]
	s_waitcnt vmcnt(8)
	ds_write_b128 v19, v[78:81] offset:57344
	v_mfma_f32_16x16x32_bf16 v[62:65], v[176:179], v[120:123], v[62:65]
	v_mfma_f32_16x16x32_bf16 v[74:77], v[180:183], v[120:123], v[74:77]
	v_mfma_f32_16x16x32_bf16 v[34:37], v[184:187], v[120:123], v[34:37]
	global_load_dwordx4 v[78:81], v250, s[6:7] offset:1792
	v_mfma_f32_16x16x32_bf16 v[54:57], v[172:175], v[148:151], v[54:57]
	s_waitcnt vmcnt(8)
	ds_write_b128 v19, v[108:111] offset:61440
	v_mfma_f32_16x16x32_bf16 v[66:69], v[176:179], v[148:151], v[66:69]
	v_mfma_f32_16x16x32_bf16 v[70:73], v[180:183], v[148:151], v[70:73]
	v_mfma_f32_16x16x32_bf16 v[38:41], v[184:187], v[148:151], v[38:41]
	s_setprio 0
	s_waitcnt lgkmcnt(0)
	s_barrier
	ds_read_b128 v[108:111], v22 offset:32768
	ds_read_b128 v[120:123], v22 offset:34816
	ds_read_b128 v[132:135], v23 offset:49152
	ds_read_b128 v[140:143], v23 offset:51200
	ds_read_b128 v[148:151], v22 offset:36864
	ds_read_b128 v[152:155], v22 offset:38912
	ds_read_b128 v[156:159], v23 offset:53248
	ds_read_b128 v[160:163], v23 offset:55296
	s_setprio 2
	global_load_dwordx4 v[168:171], v24, s[36:37] offset:1920
	s_waitcnt vmcnt(8)
	ds_write_b128 v19, v[164:167]
	ds_read_b128 v[164:167], v20 offset:32768
	ds_read_b128 v[172:175], v21 offset:49152
	s_waitcnt lgkmcnt(8)
	v_mfma_f32_16x16x32_bf16 v[42:45], v[132:135], v[108:111], v[42:45]
	s_waitcnt lgkmcnt(3)
	v_mfma_f32_16x16x32_bf16 v[26:29], v[160:163], v[108:111], v[26:29]
	v_mfma_f32_16x16x32_bf16 v[96:99], v[140:143], v[108:111], v[96:99]
	v_mfma_f32_16x16x32_bf16 v[104:107], v[156:159], v[108:111], v[104:107]
	global_load_dwordx4 v[108:111], v245, s[36:37] offset:1920
	v_mfma_f32_16x16x32_bf16 v[46:49], v[132:135], v[120:123], v[46:49]
	s_waitcnt vmcnt(8)
	ds_write_b128 v19, v[92:95] offset:4096
	v_mfma_f32_16x16x32_bf16 v[58:61], v[140:143], v[120:123], v[58:61]
	ds_read_b128 v[92:95], v20 offset:34816
	v_mfma_f32_16x16x32_bf16 v[30:33], v[160:163], v[120:123], v[30:33]
	ds_read_b128 v[176:179], v21 offset:51200
	v_mfma_f32_16x16x32_bf16 v[100:103], v[156:159], v[120:123], v[100:103]
	global_load_dwordx4 v[120:123], v246, s[36:37] offset:1920
	v_mfma_f32_16x16x32_bf16 v[50:53], v[132:135], v[148:151], v[50:53]
	s_waitcnt vmcnt(8)
	ds_write_b128 v19, v[116:119] offset:8192
	v_mfma_f32_16x16x32_bf16 v[62:65], v[140:143], v[148:151], v[62:65]
	ds_read_b128 v[116:119], v20 offset:36864
	v_mfma_f32_16x16x32_bf16 v[74:77], v[156:159], v[148:151], v[74:77]
	ds_read_b128 v[180:183], v21 offset:53248
	v_mfma_f32_16x16x32_bf16 v[34:37], v[160:163], v[148:151], v[34:37]
	v_add_u32_e32 v24, 0x30780, v24
	global_load_dwordx4 v[148:151], v24, s[36:37]
	s_waitcnt vmcnt(8)
	ds_write_b128 v19, v[144:147] offset:12288
	ds_read_b128 v[144:147], v20 offset:38912
	ds_read_b128 v[184:187], v21 offset:55296
	v_mfma_f32_16x16x32_bf16 v[54:57], v[132:135], v[152:155], v[54:57]
	v_mfma_f32_16x16x32_bf16 v[66:69], v[140:143], v[152:155], v[66:69]
	v_mfma_f32_16x16x32_bf16 v[70:73], v[156:159], v[152:155], v[70:73]
	v_mfma_f32_16x16x32_bf16 v[38:41], v[160:163], v[152:155], v[38:41]
	global_load_dwordx4 v[132:135], v18, s[6:7] offset:1920
	s_waitcnt vmcnt(8)
	ds_write_b128 v19, v[124:127] offset:16384
	s_waitcnt lgkmcnt(10)
	v_mfma_f32_16x16x32_bf16 v[42:45], v[172:175], v[164:167], v[42:45]
	s_waitcnt lgkmcnt(1)
	v_mfma_f32_16x16x32_bf16 v[24:27], v[184:187], v[164:167], v[26:29]
	v_mfma_f32_16x16x32_bf16 v[96:99], v[176:179], v[164:167], v[96:99]
	v_mfma_f32_16x16x32_bf16 v[104:107], v[180:183], v[164:167], v[104:107]
	s_nop 0
	global_load_dwordx4 v[124:127], v248, s[6:7] offset:1920
	s_waitcnt vmcnt(8)
	ds_write_b128 v19, v[136:139] offset:20480
	v_mfma_f32_16x16x32_bf16 v[46:49], v[172:175], v[92:95], v[46:49]
	v_mfma_f32_16x16x32_bf16 v[58:61], v[176:179], v[92:95], v[58:61]
	v_mfma_f32_16x16x32_bf16 v[28:31], v[184:187], v[92:95], v[30:33]
	v_mfma_f32_16x16x32_bf16 v[100:103], v[180:183], v[92:95], v[100:103]
	s_nop 1
	global_load_dwordx4 v[92:95], v249, s[6:7] offset:1920
	s_waitcnt vmcnt(8)
	ds_write_b128 v19, v[112:115] offset:24576
	v_mfma_f32_16x16x32_bf16 v[50:53], v[172:175], v[116:119], v[50:53]
	v_mfma_f32_16x16x32_bf16 v[62:65], v[176:179], v[116:119], v[62:65]
	v_mfma_f32_16x16x32_bf16 v[74:77], v[180:183], v[116:119], v[74:77]
	v_mfma_f32_16x16x32_bf16 v[32:35], v[184:187], v[116:119], v[34:37]
	v_add_u32_e32 v18, 0x30780, v18
	global_load_dwordx4 v[112:115], v18, s[6:7]
	s_waitcnt vmcnt(8)
	ds_write_b128 v19, v[78:81] offset:28672
	v_mfma_f32_16x16x32_bf16 v[54:57], v[172:175], v[144:147], v[54:57]
	v_mfma_f32_16x16x32_bf16 v[66:69], v[176:179], v[144:147], v[66:69]
	v_mfma_f32_16x16x32_bf16 v[70:73], v[180:183], v[144:147], v[70:73]
	v_mfma_f32_16x16x32_bf16 v[36:39], v[184:187], v[144:147], v[38:41]
	s_setprio 0
	s_waitcnt lgkmcnt(0)
	s_barrier
; template <int MODE>
; __device__ __forceinline__ void gemm_tile(const Params& P, int tm, int tn, unsigned char* smem) {
;     ...
; #pragma unroll
;         for (int j = 0; j < 4; ++j) acc[0][j] = __builtin_amdgcn_mfma_f32_16x16x32_bf16(gb[j], ga[0], acc[0][j], 0, 0, 0);
;         __builtin_amdgcn_sched_barrier(0);
;         if (wr_ok) *(uint4*)(nB + soff0 + 4096) = rb1;
;         if (ld_ok) rb1 = *(const uint4*)(Bb + (boff + 32u * 2048u + ko));
;         __builtin_amdgcn_sched_barrier(0);
; #pragma unroll
;         for (int j = 0; j < 4; ++j) acc[1][j] = __builtin_amdgcn_mfma_f32_16x16x32_bf16(gb[j], ga[1], acc[1][j], 0, 0, 0);
;         __builtin_amdgcn_sched_barrier(0);
;         if (wr_ok) *(uint4*)(nB + soff0 + 8192) = rb2;
;         if (ld_ok) rb2 = *(const uint4*)(Bb + (boff + 64u * 2048u + ko));
;         __builtin_amdgcn_sched_barrier(0);
; #pragma unroll
;         for (int j = 0; j < 4; ++j) acc[2][j] = __builtin_amdgcn_mfma_f32_16x16x32_bf16(gb[j], ga[2], acc[2][j], 0, 0, 0);
;         __builtin_amdgcn_sched_barrier(0);
;         if (wr_ok) *(uint4*)(nB + soff0 + 12288) = rb3;
;         if (ld_ok) rb3 = *(const uint4*)(Bb + (boff + 96u * 2048u + ko));
;         __builtin_amdgcn_sched_barrier(0);
; #pragma unroll
;         for (int j = 0; j < 4; ++j) acc[3][j] = __builtin_amdgcn_mfma_f32_16x16x32_bf16(gb[j], ga[3], acc[3][j], 0, 0, 0);
;         __builtin_amdgcn_s_setprio(0);
;         __syncthreads();
	ds_read_b128 v[78:81], v22
	ds_read_b128 v[116:119], v22 offset:2048
	ds_read_b128 v[136:139], v23 offset:16384
	ds_read_b128 v[140:143], v23 offset:18432
	ds_read_b128 v[144:147], v22 offset:4096
	ds_read_b128 v[152:155], v22 offset:6144
	ds_read_b128 v[156:159], v23 offset:20480
	ds_read_b128 v[160:163], v23 offset:22528
	s_setprio 2
	s_waitcnt vmcnt(7)
	ds_write_b128 v19, v[168:171] offset:32768
	ds_read_b128 v[164:167], v20
	ds_read_b128 v[168:171], v21 offset:16384
	s_waitcnt lgkmcnt(8)
	v_mfma_f32_16x16x32_bf16 v[40:43], v[136:139], v[78:81], v[42:45]
	s_waitcnt lgkmcnt(3)
	v_mfma_f32_16x16x32_bf16 v[24:27], v[160:163], v[78:81], v[24:27]
	v_mfma_f32_16x16x32_bf16 v[96:99], v[140:143], v[78:81], v[96:99]
	v_mfma_f32_16x16x32_bf16 v[104:107], v[156:159], v[78:81], v[104:107]
	v_mfma_f32_16x16x32_bf16 v[44:47], v[136:139], v[116:119], v[46:49]
	s_waitcnt vmcnt(6)
	ds_write_b128 v19, v[108:111] offset:36864
	v_mfma_f32_16x16x32_bf16 v[58:61], v[140:143], v[116:119], v[58:61]
	ds_read_b128 v[78:81], v20 offset:2048
	v_mfma_f32_16x16x32_bf16 v[28:31], v[160:163], v[116:119], v[28:31]
	ds_read_b128 v[108:111], v21 offset:18432
	v_mfma_f32_16x16x32_bf16 v[100:103], v[156:159], v[116:119], v[100:103]
	v_mfma_f32_16x16x32_bf16 v[48:51], v[136:139], v[144:147], v[50:53]
	s_waitcnt vmcnt(5)
	ds_write_b128 v19, v[120:123] offset:40960
	v_mfma_f32_16x16x32_bf16 v[62:65], v[140:143], v[144:147], v[62:65]
	ds_read_b128 v[116:119], v20 offset:4096
	v_mfma_f32_16x16x32_bf16 v[74:77], v[156:159], v[144:147], v[74:77]
	ds_read_b128 v[120:123], v21 offset:20480
	v_mfma_f32_16x16x32_bf16 v[32:35], v[160:163], v[144:147], v[32:35]
	v_mfma_f32_16x16x32_bf16 v[52:55], v[136:139], v[152:155], v[54:57]
	s_waitcnt vmcnt(4)
	ds_write_b128 v19, v[148:151] offset:45056
	v_mfma_f32_16x16x32_bf16 v[66:69], v[140:143], v[152:155], v[66:69]
	ds_read_b128 v[144:147], v20 offset:6144
	v_mfma_f32_16x16x32_bf16 v[70:73], v[156:159], v[152:155], v[70:73]
	ds_read_b128 v[148:151], v21 offset:22528
	v_mfma_f32_16x16x32_bf16 v[36:39], v[160:163], v[152:155], v[36:39]
	s_waitcnt vmcnt(3)
	ds_write_b128 v19, v[132:135] offset:49152
	s_waitcnt lgkmcnt(10)
	v_mfma_f32_16x16x32_bf16 v[40:43], v[168:171], v[164:167], v[40:43]
	s_waitcnt lgkmcnt(1)
	v_mfma_f32_16x16x32_bf16 v[24:27], v[148:151], v[164:167], v[24:27]
	v_mfma_f32_16x16x32_bf16 v[96:99], v[108:111], v[164:167], v[96:99]
	v_mfma_f32_16x16x32_bf16 v[104:107], v[120:123], v[164:167], v[104:107]
	v_mfma_f32_16x16x32_bf16 v[44:47], v[168:171], v[78:81], v[44:47]
	s_waitcnt vmcnt(2)
	ds_write_b128 v19, v[124:127] offset:53248
	v_mfma_f32_16x16x32_bf16 v[56:59], v[108:111], v[78:81], v[58:61]
	v_mfma_f32_16x16x32_bf16 v[28:31], v[148:151], v[78:81], v[28:31]
	v_mfma_f32_16x16x32_bf16 v[100:103], v[120:123], v[78:81], v[100:103]
	v_mfma_f32_16x16x32_bf16 v[48:51], v[168:171], v[116:119], v[48:51]
	s_waitcnt vmcnt(1)
	ds_write_b128 v19, v[92:95] offset:57344
	v_mfma_f32_16x16x32_bf16 v[60:63], v[108:111], v[116:119], v[62:65]
	v_mfma_f32_16x16x32_bf16 v[74:77], v[120:123], v[116:119], v[74:77]
	v_mfma_f32_16x16x32_bf16 v[32:35], v[148:151], v[116:119], v[32:35]
	v_mfma_f32_16x16x32_bf16 v[52:55], v[168:171], v[144:147], v[52:55]
	s_waitcnt vmcnt(0)
	ds_write_b128 v19, v[112:115] offset:61440
	v_mfma_f32_16x16x32_bf16 v[64:67], v[108:111], v[144:147], v[66:69]
	v_mfma_f32_16x16x32_bf16 v[68:71], v[120:123], v[144:147], v[70:73]
	v_mfma_f32_16x16x32_bf16 v[36:39], v[148:151], v[144:147], v[36:39]
	s_setprio 0
	s_waitcnt lgkmcnt(0)
	s_barrier
; template <int MODE>
; __device__ __forceinline__ void gemm_tile(const Params& P, int tm, int tn, unsigned char* smem) {
;     ...
; #pragma unroll
;         for (int j = 0; j < 4; ++j) acc[0][j] = __builtin_amdgcn_mfma_f32_16x16x32_bf16(gb[j], ga[0], acc[0][j], 0, 0, 0);
;         __builtin_amdgcn_sched_barrier(0);
;         if (wr_ok) *(uint4*)(nB + soff0 + 4096) = rb1;
;         if (ld_ok) rb1 = *(const uint4*)(Bb + (boff + 32u * 2048u + ko));
;         __builtin_amdgcn_sched_barrier(0);
; #pragma unroll
;         for (int j = 0; j < 4; ++j) acc[1][j] = __builtin_amdgcn_mfma_f32_16x16x32_bf16(gb[j], ga[1], acc[1][j], 0, 0, 0);
;         __builtin_amdgcn_sched_barrier(0);
;         if (wr_ok) *(uint4*)(nB + soff0 + 8192) = rb2;
;         if (ld_ok) rb2 = *(const uint4*)(Bb + (boff + 64u * 2048u + ko));
;         __builtin_amdgcn_sched_barrier(0);
; #pragma unroll
;         for (int j = 0; j < 4; ++j) acc[2][j] = __builtin_amdgcn_mfma_f32_16x16x32_bf16(gb[j], ga[2], acc[2][j], 0, 0, 0);
;         __builtin_amdgcn_sched_barrier(0);
;         if (wr_ok) *(uint4*)(nB + soff0 + 12288) = rb3;
;         if (ld_ok) rb3 = *(const uint4*)(Bb + (boff + 96u * 2048u + ko));
;         __builtin_amdgcn_sched_barrier(0);
; #pragma unroll
;         for (int j = 0; j < 4; ++j) acc[3][j] = __builtin_amdgcn_mfma_f32_16x16x32_bf16(gb[j], ga[3], acc[3][j], 0, 0, 0);
;         __builtin_amdgcn_s_setprio(0);
;         __syncthreads();
;     }
;     ...
;         const int hp = tn;
;         float rs[4];
; #pragma unroll
;         for (int i = 0; i < 4; ++i) {
;             const int row = m0 + wr * 64 + 16 * i + lr;
;             const float4 sp = i == 0 ? ssp0 : i == 1 ? ssp1 : i == 2 ? ssp2 : ssp3;
;             const float s = x4_sum((sp.x + sp.y) + (sp.z + sp.w));
;             rs[i] = rsqrtf(s * (1.0f / DM) + EPS);
;             if (tn == 0 && wc == 0 && g == 0) ((float*)(P.ws + WS_RSTD))[row] = rs[i];
;         }
	ds_read_b128 v[78:81], v22 offset:32768
	ds_read_b128 v[92:95], v22 offset:34816
	ds_read_b128 v[108:111], v23 offset:49152
	ds_read_b128 v[112:115], v23 offset:51200
	ds_read_b128 v[116:119], v22 offset:36864
	ds_read_b128 v[120:123], v22 offset:38912
	ds_read_b128 v[124:127], v23 offset:53248
	ds_read_b128 v[132:135], v23 offset:55296
	s_setprio 2
	ds_read_b128 v[136:139], v20 offset:32768
	ds_read_b128 v[140:143], v21 offset:49152
	s_waitcnt lgkmcnt(7)
	v_mfma_f32_16x16x32_bf16 v[40:43], v[108:111], v[78:81], v[40:43]
	s_waitcnt lgkmcnt(2)
	v_mfma_f32_16x16x32_bf16 v[22:25], v[132:135], v[78:81], v[24:27]
	v_mfma_f32_16x16x32_bf16 v[96:99], v[112:115], v[78:81], v[96:99]
	v_mfma_f32_16x16x32_bf16 v[104:107], v[124:127], v[78:81], v[104:107]
	v_mfma_f32_16x16x32_bf16 v[44:47], v[108:111], v[92:95], v[44:47]
	ds_read_b128 v[144:147], v20 offset:34816
	v_mfma_f32_16x16x32_bf16 v[56:59], v[112:115], v[92:95], v[56:59]
	ds_read_b128 v[148:151], v21 offset:51200
	v_mfma_f32_16x16x32_bf16 v[26:29], v[132:135], v[92:95], v[28:31]
	v_mfma_f32_16x16x32_bf16 v[100:103], v[124:127], v[92:95], v[100:103]
	v_mfma_f32_16x16x32_bf16 v[30:33], v[132:135], v[116:119], v[32:35]
	ds_read_b128 v[92:95], v20 offset:36864
	v_mfma_f32_16x16x32_bf16 v[156:159], v[108:111], v[116:119], v[48:51]
	ds_read_b128 v[152:155], v21 offset:53248
	v_mfma_f32_16x16x32_bf16 v[160:163], v[112:115], v[116:119], v[60:63]
	v_mfma_f32_16x16x32_bf16 v[164:167], v[124:127], v[116:119], v[74:77]
	v_mfma_f32_16x16x32_bf16 v[108:111], v[108:111], v[120:123], v[52:55]
	ds_read_b128 v[116:119], v20 offset:38912
	v_mfma_f32_16x16x32_bf16 v[112:115], v[112:115], v[120:123], v[64:67]
	ds_read_b128 v[18:21], v21 offset:55296
	v_mfma_f32_16x16x32_bf16 v[124:127], v[124:127], v[120:123], v[68:71]
	v_mfma_f32_16x16x32_bf16 v[120:123], v[132:135], v[120:123], v[36:39]
	s_waitcnt lgkmcnt(6)
	v_mfma_f32_16x16x32_bf16 v[78:81], v[140:143], v[136:139], v[40:43]
	s_waitcnt lgkmcnt(4)
	v_mfma_f32_16x16x32_bf16 v[74:77], v[148:151], v[136:139], v[96:99]
	s_waitcnt lgkmcnt(2)
	v_mfma_f32_16x16x32_bf16 v[70:73], v[152:155], v[136:139], v[104:107]
	s_waitcnt lgkmcnt(0)
	v_mfma_f32_16x16x32_bf16 v[66:69], v[18:21], v[136:139], v[22:25]
	v_mfma_f32_16x16x32_bf16 v[62:65], v[140:143], v[144:147], v[44:47]
	v_mfma_f32_16x16x32_bf16 v[58:61], v[148:151], v[144:147], v[56:59]
	v_mfma_f32_16x16x32_bf16 v[54:57], v[152:155], v[144:147], v[100:103]
	v_mfma_f32_16x16x32_bf16 v[50:53], v[18:21], v[144:147], v[26:29]
	v_mfma_f32_16x16x32_bf16 v[46:49], v[140:143], v[92:95], v[156:159]
	v_mfma_f32_16x16x32_bf16 v[42:45], v[148:151], v[92:95], v[160:163]
	v_mfma_f32_16x16x32_bf16 v[38:41], v[152:155], v[92:95], v[164:167]
	v_mfma_f32_16x16x32_bf16 v[34:37], v[18:21], v[92:95], v[30:33]
	v_mfma_f32_16x16x32_bf16 v[30:33], v[140:143], v[116:119], v[108:111]
	v_mfma_f32_16x16x32_bf16 v[26:29], v[148:151], v[116:119], v[112:115]
	v_mfma_f32_16x16x32_bf16 v[22:25], v[152:155], v[116:119], v[124:127]
	v_mfma_f32_16x16x32_bf16 v[18:21], v[18:21], v[116:119], v[120:123]
	s_setprio 0
	v_add_f32_e32 v10, v10, v11
	v_add_f32_e32 v11, v12, v13
	v_add_f32_e32 v10, v10, v11
	v_mov_b32_e32 v11, v10
	s_nop 1
	v_permlane32_swap_b32_e32 v10, v11
	v_add_f32_e32 v10, v10, v11
	v_mov_b32_e32 v11, v10
	s_nop 1
	v_permlane16_swap_b32_e32 v10, v11
	v_add_f32_e32 v10, v10, v11
	v_fmamk_f32 v10, v10, 0x3a800000, v86
	v_mul_f32_e32 v11, 0x4b800000, v10
	v_cmp_gt_f32_e64 s[0:1], s19, v10
	v_lshl_add_u64 v[84:85], v[84:85], 2, s[8:9]
	s_nop 0
	v_cndmask_b32_e64 v10, v10, v11, s[0:1]
	v_rsq_f32_e32 v10, v10
	v_or3_b32 v11, v91, s2, v89
	v_cmp_eq_u32_e32 vcc, 0, v11
	s_barrier
	v_mul_f32_e32 v11, 0x45800000, v10
	v_cndmask_b32_e64 v12, v10, v11, s[0:1]
	s_and_saveexec_b64 s[0:1], vcc
	s_cbranch_execz .LBB0_1265
	global_store_dword v[84:85], v12, off
